# log-forget plane stored as log2 f (bf16) instead of ln f; scan exponentiates with 2^x directly: 19 multiplies per thread per chunk and 2 packed multiplies per gate block removed (same values mathemati
# baseline (speedup 1.0000x reference)
.LBB0_143:
	s_add_i32 s6, s6, s50
	v_add_u32_e32 v131, s6, v213
	v_ashrrev_i32_e32 v133, 11, v131
	v_cmp_lt_u32_e32 vcc, s24, v131
	v_cmp_ne_u32_e64 s[0:1], 4, v133
	s_mov_b32 s52, s7
	v_and_b32_e32 v130, 0x7ff, v131
	s_and_b64 s[44:45], vcc, s[0:1]
	s_and_saveexec_b64 s[0:1], s[44:45]
	s_xor_b64 s[0:1], exec, s[0:1]
	s_cbranch_execz .LBB0_147
	v_cmp_ne_u32_e32 vcc, 3, v133
	s_and_saveexec_b64 s[2:3], vcc
	s_cbranch_execz .LBB0_146
	v_and_b32_e32 v128, 0xfffff800, v131
	v_add_u32_e32 v128, 0xfffff800, v128
	v_ashrrev_i32_e32 v129, 31, v128
	v_lshl_add_u64 v[128:129], v[128:129], 2, s[90:91]
	v_lshlrev_b32_e32 v176, 2, v130
	v_lshl_add_u64 v[128:129], v[128:129], 0, v[176:177]
	global_load_dwordx4 v[134:137], v[128:129], off
	v_mul_f32_e32 v124, 0xbfb8aa3b, v124
	v_exp_f32_e32 v124, v124
	v_mul_f32_e32 v125, 0xbfb8aa3b, v125
	v_exp_f32_e32 v125, v125
	v_mul_f32_e32 v126, 0xbfb8aa3b, v126
	v_exp_f32_e32 v126, v126
	v_mul_f32_e32 v127, 0xbfb8aa3b, v127
	v_exp_f32_e32 v127, v127
	v_add_f32_e32 v124, 1.0, v124
	v_rcp_f32_e32 v124, v124
	v_add_f32_e32 v125, 1.0, v125
	v_rcp_f32_e32 v125, v125
	v_add_f32_e32 v126, 1.0, v126
	v_rcp_f32_e32 v126, v126
	v_add_f32_e32 v127, 1.0, v127
	v_rcp_f32_e32 v127, v127
	s_waitcnt vmcnt(0)
	v_mov_b64_e32 v[144:145], v[134:135]
	v_mov_b64_e32 v[146:147], v[136:137]
	v_sub_f32_e32 v128, 1.0, v134
	v_fma_f32 v124, v124, v128, v134
	v_sub_f32_e32 v128, 1.0, v135
	v_fma_f32 v125, v125, v128, v135
	v_sub_f32_e32 v128, 1.0, v136
	v_fma_f32 v126, v126, v128, v136
	v_sub_f32_e32 v128, 1.0, v137
	v_fmac_f32_e32 v137, v127, v128
	v_log_f32_e32 v124, v124
	v_log_f32_e32 v125, v125
	v_log_f32_e32 v126, v126
	v_log_f32_e32 v127, v137
.LBB0_146:
	s_or_b64 exec, exec, s[2:3]

.LBB0_149:
	s_or_b64 exec, exec, s[0:1]
	v_add_u32_e32 v134, 16, v131
	v_ashrrev_i32_e32 v135, 11, v134
	v_cmp_lt_u32_e32 vcc, s24, v134
	v_cmp_ne_u32_e64 s[0:1], 4, v135
	v_and_b32_e32 v132, 0x7ff, v134
	s_and_b64 s[46:47], vcc, s[0:1]
	s_and_saveexec_b64 s[0:1], s[46:47]
	s_xor_b64 s[0:1], exec, s[0:1]
	s_cbranch_execz .LBB0_153
	v_cmp_ne_u32_e32 vcc, 3, v135
	s_and_saveexec_b64 s[2:3], vcc
	s_cbranch_execz .LBB0_152
	v_and_b32_e32 v128, 0xfffff800, v134
	v_add_u32_e32 v128, 0xfffff800, v128
	v_ashrrev_i32_e32 v129, 31, v128
	v_lshl_add_u64 v[128:129], v[128:129], 2, s[90:91]
	v_lshlrev_b32_e32 v176, 2, v132
	v_lshl_add_u64 v[128:129], v[128:129], 0, v[176:177]
	global_load_dwordx4 v[136:139], v[128:129], off
	v_mul_f32_e32 v120, 0xbfb8aa3b, v120
	v_exp_f32_e32 v120, v120
	v_mul_f32_e32 v121, 0xbfb8aa3b, v121
	v_exp_f32_e32 v121, v121
	v_mul_f32_e32 v122, 0xbfb8aa3b, v122
	v_exp_f32_e32 v122, v122
	v_mul_f32_e32 v123, 0xbfb8aa3b, v123
	v_exp_f32_e32 v123, v123
	v_add_f32_e32 v120, 1.0, v120
	v_rcp_f32_e32 v120, v120
	v_add_f32_e32 v121, 1.0, v121
	v_rcp_f32_e32 v121, v121
	v_add_f32_e32 v122, 1.0, v122
	v_rcp_f32_e32 v122, v122
	v_add_f32_e32 v123, 1.0, v123
	v_rcp_f32_e32 v123, v123
	s_waitcnt vmcnt(0)
	v_mov_b64_e32 v[148:149], v[136:137]
	v_mov_b64_e32 v[150:151], v[138:139]
	v_sub_f32_e32 v128, 1.0, v136
	v_fma_f32 v120, v120, v128, v136
	v_sub_f32_e32 v128, 1.0, v137
	v_fma_f32 v121, v121, v128, v137
	v_sub_f32_e32 v128, 1.0, v138
	v_fma_f32 v122, v122, v128, v138
	v_sub_f32_e32 v128, 1.0, v139
	v_fmac_f32_e32 v139, v123, v128
	v_log_f32_e32 v120, v120
	v_log_f32_e32 v121, v121
	v_log_f32_e32 v122, v122
	v_log_f32_e32 v123, v139
.LBB0_152:
	s_or_b64 exec, exec, s[2:3]

.LBB0_155:
	s_or_b64 exec, exec, s[0:1]
	v_cvt_pk_bf16_f32 v138, v120, v121
	v_add_u32_e32 v120, s6, v215
	v_add_u32_e32 v128, s48, v214
	v_cvt_pk_bf16_f32 v139, v122, v123
	v_ashrrev_i32_e32 v122, 11, v120
	v_ashrrev_i32_e32 v129, 31, v128
	v_cvt_pk_bf16_f32 v136, v124, v125
	v_and_b32_e32 v124, 0x7ff, v120
	v_mul_hi_i32_i24_e32 v121, 0x4400, v122
	v_mul_i32_i24_e32 v120, 0x4400, v122
	v_lshl_add_u64 v[122:123], v[120:121], 0, v[128:129]
	v_lshlrev_b64 v[122:123], 12, v[122:123]
	v_cvt_pk_bf16_f32 v137, v126, v127
	v_lshl_add_u64 v[122:123], s[86:87], 0, v[122:123]
	v_lshlrev_b32_e32 v176, 1, v124
	v_permlane16_swap_b32_e32 v136, v138
	v_permlane16_swap_b32_e32 v137, v139
	v_lshl_add_u64 v[122:123], v[122:123], 0, v[176:177]
	s_add_i32 s6, s6, 32
	global_store_dwordx4 v[122:123], v[136:139], off
	v_add_u32_e32 v123, s6, v213
	v_ashrrev_i32_e32 v126, 11, v123
	v_cmp_lt_u32_e32 vcc, s24, v123
	v_cmp_ne_u32_e64 s[0:1], 4, v126
	v_and_b32_e32 v122, 0x7ff, v123
	s_and_b64 s[48:49], vcc, s[0:1]
	s_and_saveexec_b64 s[0:1], s[48:49]
	s_xor_b64 s[0:1], exec, s[0:1]
	s_cbranch_execz .LBB0_159
	v_cmp_ne_u32_e32 vcc, 3, v126
	s_and_saveexec_b64 s[2:3], vcc
	s_cbranch_execz .LBB0_158
	v_and_b32_e32 v124, 0xfffff800, v123
	v_add_u32_e32 v124, 0xfffff800, v124
	v_ashrrev_i32_e32 v125, 31, v124
	v_lshl_add_u64 v[124:125], v[124:125], 2, s[90:91]
	v_lshlrev_b32_e32 v136, 2, v122
	v_mov_b32_e32 v137, v177
	v_lshl_add_u64 v[124:125], v[124:125], 0, v[136:137]
	global_load_dwordx4 v[136:139], v[124:125], off
	v_mul_f32_e32 v116, 0xbfb8aa3b, v116
	v_exp_f32_e32 v116, v116
	v_mul_f32_e32 v117, 0xbfb8aa3b, v117
	v_exp_f32_e32 v117, v117
	v_mul_f32_e32 v118, 0xbfb8aa3b, v118
	v_exp_f32_e32 v118, v118
	v_mul_f32_e32 v119, 0xbfb8aa3b, v119
	v_exp_f32_e32 v119, v119
	v_add_f32_e32 v116, 1.0, v116
	v_rcp_f32_e32 v116, v116
	v_add_f32_e32 v117, 1.0, v117
	v_rcp_f32_e32 v117, v117
	v_add_f32_e32 v118, 1.0, v118
	v_rcp_f32_e32 v118, v118
	v_add_f32_e32 v119, 1.0, v119
	v_rcp_f32_e32 v119, v119
	s_waitcnt vmcnt(0)
	v_mov_b64_e32 v[152:153], v[136:137]
	v_mov_b64_e32 v[154:155], v[138:139]
	v_sub_f32_e32 v124, 1.0, v136
	v_fma_f32 v116, v116, v124, v136
	v_sub_f32_e32 v124, 1.0, v137
	v_fma_f32 v117, v117, v124, v137
	v_sub_f32_e32 v124, 1.0, v138
	v_fma_f32 v118, v118, v124, v138
	v_sub_f32_e32 v124, 1.0, v139
	v_fmac_f32_e32 v139, v119, v124
	v_log_f32_e32 v116, v116
	v_log_f32_e32 v117, v117
	v_log_f32_e32 v118, v118
	v_log_f32_e32 v119, v139
.LBB0_158:
	s_or_b64 exec, exec, s[2:3]

.LBB0_161:
	s_or_b64 exec, exec, s[0:1]
	v_add_u32_e32 v125, 16, v123
	v_ashrrev_i32_e32 v127, 11, v125
	v_cmp_lt_u32_e32 vcc, s24, v125
	v_cmp_ne_u32_e64 s[0:1], 4, v127
	v_and_b32_e32 v124, 0x7ff, v125
	s_and_b64 s[0:1], vcc, s[0:1]
	s_and_saveexec_b64 s[2:3], s[0:1]
	s_xor_b64 s[2:3], exec, s[2:3]
	s_cbranch_execz .LBB0_165
	v_cmp_ne_u32_e32 vcc, 3, v127
	s_and_saveexec_b64 s[8:9], vcc
	s_cbranch_execz .LBB0_164
	v_and_b32_e32 v136, 0xfffff800, v125
	v_add_u32_e32 v136, 0xfffff800, v136
	v_ashrrev_i32_e32 v137, 31, v136
	v_lshl_add_u64 v[136:137], v[136:137], 2, s[90:91]
	v_lshlrev_b32_e32 v138, 2, v124
	v_mov_b32_e32 v139, v177
	v_lshl_add_u64 v[136:137], v[136:137], 0, v[138:139]
	global_load_dwordx4 v[136:139], v[136:137], off
	v_mul_f32_e32 v112, 0xbfb8aa3b, v112
	v_exp_f32_e32 v112, v112
	v_mul_f32_e32 v113, 0xbfb8aa3b, v113
	v_exp_f32_e32 v113, v113
	v_mul_f32_e32 v114, 0xbfb8aa3b, v114
	v_exp_f32_e32 v114, v114
	v_mul_f32_e32 v115, 0xbfb8aa3b, v115
	v_exp_f32_e32 v115, v115
	v_add_f32_e32 v112, 1.0, v112
	v_rcp_f32_e32 v112, v112
	v_add_f32_e32 v113, 1.0, v113
	v_rcp_f32_e32 v113, v113
	v_add_f32_e32 v114, 1.0, v114
	v_rcp_f32_e32 v114, v114
	v_add_f32_e32 v115, 1.0, v115
	v_rcp_f32_e32 v115, v115
	s_waitcnt vmcnt(0)
	v_mov_b64_e32 v[156:157], v[136:137]
	v_mov_b64_e32 v[158:159], v[138:139]
	v_sub_f32_e32 v140, 1.0, v136
	v_fma_f32 v112, v112, v140, v136
	v_sub_f32_e32 v136, 1.0, v137
	v_fma_f32 v113, v113, v136, v137
	v_sub_f32_e32 v136, 1.0, v138
	v_fma_f32 v114, v114, v136, v138
	v_sub_f32_e32 v136, 1.0, v139
	v_fmac_f32_e32 v139, v115, v136
	v_log_f32_e32 v112, v112
	v_log_f32_e32 v113, v113
	v_log_f32_e32 v114, v114
	v_log_f32_e32 v115, v139
.LBB0_164:
	s_or_b64 exec, exec, s[8:9]

.LBB0_167:
	s_or_b64 exec, exec, s[2:3]
	v_cvt_pk_bf16_f32 v138, v112, v113
	v_add_u32_e32 v112, s6, v215
	v_cvt_pk_bf16_f32 v139, v114, v115
	v_ashrrev_i32_e32 v114, 11, v112
	v_cvt_pk_bf16_f32 v137, v118, v119
	v_and_b32_e32 v118, 0x7ff, v112
	v_mul_hi_i32_i24_e32 v113, 0x4400, v114
	v_mul_i32_i24_e32 v112, 0x4400, v114
	v_lshl_add_u64 v[114:115], v[112:113], 0, v[128:129]
	v_lshlrev_b64 v[114:115], 12, v[114:115]
	v_cvt_pk_bf16_f32 v136, v116, v117
	v_lshl_add_u64 v[116:117], s[86:87], 0, v[114:115]
	v_lshlrev_b32_e32 v114, 1, v118
	v_mov_b32_e32 v115, v177
	v_permlane16_swap_b32_e32 v136, v138
	v_permlane16_swap_b32_e32 v137, v139
	v_lshl_add_u64 v[116:117], v[116:117], 0, v[114:115]
	global_store_dwordx4 v[116:117], v[136:139], off
	s_and_saveexec_b64 s[2:3], s[44:45]
	s_xor_b64 s[2:3], exec, s[2:3]
	s_cbranch_execz .LBB0_175
	v_cmp_ne_u32_e32 vcc, 3, v133
	s_and_saveexec_b64 s[8:9], vcc
	s_cbranch_execz .LBB0_170
	v_and_b32_e32 v115, 0xfffff800, v131
	v_add_u32_e32 v116, 0xfffff800, v115
	v_ashrrev_i32_e32 v117, 31, v116
	v_lshl_add_u64 v[116:117], v[116:117], 2, s[90:91]
	v_lshlrev_b32_e32 v118, 2, v130
	v_mov_b32_e32 v119, v177
	v_lshl_add_u64 v[116:117], v[116:117], 0, v[118:119]
	v_mov_b64_e32 v[116:117], v[144:145]
	v_mov_b64_e32 v[118:119], v[146:147]
	v_mul_f32_e32 v108, 0xbfb8aa3b, v108
	v_exp_f32_e32 v108, v108
	v_mul_f32_e32 v109, 0xbfb8aa3b, v109
	v_exp_f32_e32 v109, v109
	v_mul_f32_e32 v110, 0xbfb8aa3b, v110
	v_exp_f32_e32 v110, v110
	v_mul_f32_e32 v111, 0xbfb8aa3b, v111
	v_exp_f32_e32 v111, v111
	v_add_f32_e32 v108, 1.0, v108
	v_rcp_f32_e32 v108, v108
	v_add_f32_e32 v109, 1.0, v109
	v_rcp_f32_e32 v109, v109
	v_add_f32_e32 v110, 1.0, v110
	v_rcp_f32_e32 v110, v110
	v_add_f32_e32 v111, 1.0, v111
	v_rcp_f32_e32 v111, v111
	v_sub_f32_e32 v115, 1.0, v116
	v_fma_f32 v108, v108, v115, v116
	v_sub_f32_e32 v115, 1.0, v117
	v_fma_f32 v109, v109, v115, v117
	v_sub_f32_e32 v115, 1.0, v118
	v_fma_f32 v110, v110, v115, v118
	v_sub_f32_e32 v115, 1.0, v119
	v_fmac_f32_e32 v119, v111, v115
	v_log_f32_e32 v108, v108
	v_log_f32_e32 v109, v109
	v_log_f32_e32 v110, v110
	v_log_f32_e32 v111, v119
.LBB0_170:
	s_or_b64 exec, exec, s[8:9]
	s_andn2_saveexec_b64 s[2:3], s[2:3]
	s_cbranch_execnz .LBB0_176

.LBB0_172:
	v_cmp_ne_u32_e32 vcc, 3, v135
	s_and_saveexec_b64 s[8:9], vcc
	s_cbranch_execz .LBB0_174
	v_and_b32_e32 v115, 0xfffff800, v134
	v_add_u32_e32 v116, 0xfffff800, v115
	v_ashrrev_i32_e32 v117, 31, v116
	v_lshl_add_u64 v[116:117], v[116:117], 2, s[90:91]
	v_lshlrev_b32_e32 v118, 2, v132
	v_mov_b32_e32 v119, v177
	v_lshl_add_u64 v[116:117], v[116:117], 0, v[118:119]
	v_mov_b64_e32 v[116:117], v[148:149]
	v_mov_b64_e32 v[118:119], v[150:151]
	v_mul_f32_e32 v104, 0xbfb8aa3b, v104
	v_exp_f32_e32 v104, v104
	v_mul_f32_e32 v105, 0xbfb8aa3b, v105
	v_exp_f32_e32 v105, v105
	v_mul_f32_e32 v106, 0xbfb8aa3b, v106
	v_exp_f32_e32 v106, v106
	v_mul_f32_e32 v107, 0xbfb8aa3b, v107
	v_exp_f32_e32 v107, v107
	v_add_f32_e32 v104, 1.0, v104
	v_rcp_f32_e32 v104, v104
	v_add_f32_e32 v105, 1.0, v105
	v_rcp_f32_e32 v105, v105
	v_add_f32_e32 v106, 1.0, v106
	v_rcp_f32_e32 v106, v106
	v_add_f32_e32 v107, 1.0, v107
	v_rcp_f32_e32 v107, v107
	v_sub_f32_e32 v115, 1.0, v116
	v_fma_f32 v104, v104, v115, v116
	v_sub_f32_e32 v115, 1.0, v117
	v_fma_f32 v105, v105, v115, v117
	v_sub_f32_e32 v115, 1.0, v118
	v_fma_f32 v106, v106, v115, v118
	v_sub_f32_e32 v115, 1.0, v119
	v_fmac_f32_e32 v119, v107, v115
	v_log_f32_e32 v104, v104
	v_log_f32_e32 v105, v105
	v_log_f32_e32 v106, v106
	v_log_f32_e32 v107, v119
.LBB0_174:
	s_or_b64 exec, exec, s[8:9]
	s_andn2_saveexec_b64 s[2:3], s[2:3]
	s_cbranch_execnz .LBB0_178
	s_branch .LBB0_179

.LBB0_179:
	s_or_b64 exec, exec, s[2:3]
	v_add_u32_e32 v116, 16, v128
	v_ashrrev_i32_e32 v117, 31, v116
	v_cvt_pk_bf16_f32 v138, v104, v105
	v_lshl_add_u64 v[104:105], v[120:121], 0, v[116:117]
	v_lshlrev_b64 v[104:105], 12, v[104:105]
	v_cvt_pk_bf16_f32 v137, v110, v111
	v_cvt_pk_bf16_f32 v136, v108, v109
	v_cvt_pk_bf16_f32 v139, v106, v107
	v_lshl_add_u64 v[104:105], s[86:87], 0, v[104:105]
	v_permlane16_swap_b32_e32 v136, v138
	v_permlane16_swap_b32_e32 v137, v139
	v_lshl_add_u64 v[104:105], v[104:105], 0, v[176:177]
	global_store_dwordx4 v[104:105], v[136:139], off
	s_and_saveexec_b64 s[2:3], s[48:49]
	s_xor_b64 s[2:3], exec, s[2:3]
	s_cbranch_execz .LBB0_187
	v_cmp_ne_u32_e32 vcc, 3, v126
	s_and_saveexec_b64 s[8:9], vcc
	s_cbranch_execz .LBB0_182
	v_and_b32_e32 v104, 0xfffff800, v123
	v_add_u32_e32 v104, 0xfffff800, v104
	v_ashrrev_i32_e32 v105, 31, v104
	v_lshl_add_u64 v[104:105], v[104:105], 2, s[90:91]
	v_lshlrev_b32_e32 v106, 2, v122
	v_mov_b32_e32 v107, v177
	v_lshl_add_u64 v[104:105], v[104:105], 0, v[106:107]
	v_mov_b64_e32 v[104:105], v[152:153]
	v_mov_b64_e32 v[106:107], v[154:155]
	v_mul_f32_e32 v100, 0xbfb8aa3b, v100
	v_exp_f32_e32 v100, v100
	v_mul_f32_e32 v101, 0xbfb8aa3b, v101
	v_exp_f32_e32 v101, v101
	v_mul_f32_e32 v102, 0xbfb8aa3b, v102
	v_exp_f32_e32 v102, v102
	v_mul_f32_e32 v103, 0xbfb8aa3b, v103
	v_exp_f32_e32 v103, v103
	v_add_f32_e32 v100, 1.0, v100
	v_rcp_f32_e32 v100, v100
	v_add_f32_e32 v101, 1.0, v101
	v_rcp_f32_e32 v101, v101
	v_add_f32_e32 v102, 1.0, v102
	v_rcp_f32_e32 v102, v102
	v_add_f32_e32 v103, 1.0, v103
	v_rcp_f32_e32 v103, v103
	v_sub_f32_e32 v108, 1.0, v104
	v_fma_f32 v100, v100, v108, v104
	v_sub_f32_e32 v104, 1.0, v105
	v_fma_f32 v101, v101, v104, v105
	v_sub_f32_e32 v104, 1.0, v106
	v_fma_f32 v102, v102, v104, v106
	v_sub_f32_e32 v104, 1.0, v107
	v_fmac_f32_e32 v107, v103, v104
	v_log_f32_e32 v100, v100
	v_log_f32_e32 v101, v101
	v_log_f32_e32 v102, v102
	v_log_f32_e32 v103, v107
.LBB0_182:
	s_or_b64 exec, exec, s[8:9]
	s_andn2_saveexec_b64 s[2:3], s[2:3]
	s_cbranch_execnz .LBB0_188

.LBB0_184:
	v_cmp_ne_u32_e32 vcc, 3, v127
	s_and_saveexec_b64 s[8:9], vcc
	s_cbranch_execz .LBB0_186
	v_and_b32_e32 v104, 0xfffff800, v125
	v_add_u32_e32 v104, 0xfffff800, v104
	v_ashrrev_i32_e32 v105, 31, v104
	v_lshl_add_u64 v[104:105], v[104:105], 2, s[90:91]
	v_lshlrev_b32_e32 v106, 2, v124
	v_mov_b32_e32 v107, v177
	v_lshl_add_u64 v[104:105], v[104:105], 0, v[106:107]
	v_mov_b64_e32 v[104:105], v[156:157]
	v_mov_b64_e32 v[106:107], v[158:159]
	v_mul_f32_e32 v96, 0xbfb8aa3b, v96
	v_exp_f32_e32 v96, v96
	v_mul_f32_e32 v97, 0xbfb8aa3b, v97
	v_exp_f32_e32 v97, v97
	v_mul_f32_e32 v98, 0xbfb8aa3b, v98
	v_exp_f32_e32 v98, v98
	v_mul_f32_e32 v99, 0xbfb8aa3b, v99
	v_exp_f32_e32 v99, v99
	v_add_f32_e32 v96, 1.0, v96
	v_rcp_f32_e32 v96, v96
	v_add_f32_e32 v97, 1.0, v97
	v_rcp_f32_e32 v97, v97
	v_add_f32_e32 v98, 1.0, v98
	v_rcp_f32_e32 v98, v98
	v_add_f32_e32 v99, 1.0, v99
	v_rcp_f32_e32 v99, v99
	v_sub_f32_e32 v108, 1.0, v104
	v_fma_f32 v96, v96, v108, v104
	v_sub_f32_e32 v104, 1.0, v105
	v_fma_f32 v97, v97, v104, v105
	v_sub_f32_e32 v104, 1.0, v106
	v_fma_f32 v98, v98, v104, v106
	v_sub_f32_e32 v104, 1.0, v107
	v_fmac_f32_e32 v107, v99, v104
	v_log_f32_e32 v96, v96
	v_log_f32_e32 v97, v97
	v_log_f32_e32 v98, v98
	v_log_f32_e32 v99, v107
.LBB0_186:
	s_or_b64 exec, exec, s[8:9]
	s_andn2_saveexec_b64 s[2:3], s[2:3]
	s_cbranch_execnz .LBB0_190
	s_branch .LBB0_191

.LBB0_191:
	s_or_b64 exec, exec, s[2:3]
	v_cvt_pk_bf16_f32 v104, v96, v97
	v_lshl_add_u64 v[96:97], v[112:113], 0, v[116:117]
	v_lshlrev_b64 v[96:97], 12, v[96:97]
	v_cvt_pk_bf16_f32 v103, v102, v103
	v_cvt_pk_bf16_f32 v102, v100, v101
	v_cvt_pk_bf16_f32 v105, v98, v99
	v_lshl_add_u64 v[96:97], s[86:87], 0, v[96:97]
	v_mov_b32_e32 v115, v177
	v_permlane16_swap_b32_e32 v102, v104
	v_permlane16_swap_b32_e32 v103, v105
	v_lshl_add_u64 v[96:97], v[96:97], 0, v[114:115]
	global_store_dwordx4 v[96:97], v[102:105], off
	s_and_saveexec_b64 s[2:3], s[44:45]
	s_xor_b64 s[2:3], exec, s[2:3]
	s_cbranch_execz .LBB0_199
	v_cmp_ne_u32_e32 vcc, 3, v133
	s_and_saveexec_b64 s[8:9], vcc
	s_cbranch_execz .LBB0_194
	v_and_b32_e32 v96, 0xfffff800, v131
	v_add_u32_e32 v96, 0xfffff800, v96
	v_ashrrev_i32_e32 v97, 31, v96
	v_lshl_add_u64 v[96:97], v[96:97], 2, s[90:91]
	v_lshlrev_b32_e32 v98, 2, v130
	v_mov_b32_e32 v99, v177
	v_lshl_add_u64 v[96:97], v[96:97], 0, v[98:99]
	v_mov_b64_e32 v[96:97], v[144:145]
	v_mov_b64_e32 v[98:99], v[146:147]
	v_mul_f32_e32 v92, 0xbfb8aa3b, v92
	v_exp_f32_e32 v92, v92
	v_mul_f32_e32 v93, 0xbfb8aa3b, v93
	v_exp_f32_e32 v93, v93
	v_mul_f32_e32 v94, 0xbfb8aa3b, v94
	v_exp_f32_e32 v94, v94
	v_mul_f32_e32 v95, 0xbfb8aa3b, v95
	v_exp_f32_e32 v95, v95
	v_add_f32_e32 v92, 1.0, v92
	v_rcp_f32_e32 v92, v92
	v_add_f32_e32 v93, 1.0, v93
	v_rcp_f32_e32 v93, v93
	v_add_f32_e32 v94, 1.0, v94
	v_rcp_f32_e32 v94, v94
	v_add_f32_e32 v95, 1.0, v95
	v_rcp_f32_e32 v95, v95
	v_sub_f32_e32 v100, 1.0, v96
	v_fma_f32 v92, v92, v100, v96
	v_sub_f32_e32 v96, 1.0, v97
	v_fma_f32 v93, v93, v96, v97
	v_sub_f32_e32 v96, 1.0, v98
	v_fma_f32 v94, v94, v96, v98
	v_sub_f32_e32 v96, 1.0, v99
	v_fmac_f32_e32 v99, v95, v96
	v_log_f32_e32 v92, v92
	v_log_f32_e32 v93, v93
	v_log_f32_e32 v94, v94
	v_log_f32_e32 v95, v99
.LBB0_194:
	s_or_b64 exec, exec, s[8:9]
	s_andn2_saveexec_b64 s[2:3], s[2:3]
	s_cbranch_execnz .LBB0_200

.LBB0_196:
	v_cmp_ne_u32_e32 vcc, 3, v135
	s_and_saveexec_b64 s[8:9], vcc
	s_cbranch_execz .LBB0_198
	v_and_b32_e32 v96, 0xfffff800, v134
	v_add_u32_e32 v96, 0xfffff800, v96
	v_ashrrev_i32_e32 v97, 31, v96
	v_lshl_add_u64 v[96:97], v[96:97], 2, s[90:91]
	v_lshlrev_b32_e32 v98, 2, v132
	v_mov_b32_e32 v99, v177
	v_lshl_add_u64 v[96:97], v[96:97], 0, v[98:99]
	v_mov_b64_e32 v[96:97], v[148:149]
	v_mov_b64_e32 v[98:99], v[150:151]
	v_mul_f32_e32 v88, 0xbfb8aa3b, v88
	v_exp_f32_e32 v88, v88
	v_mul_f32_e32 v89, 0xbfb8aa3b, v89
	v_exp_f32_e32 v89, v89
	v_mul_f32_e32 v90, 0xbfb8aa3b, v90
	v_exp_f32_e32 v90, v90
	v_mul_f32_e32 v91, 0xbfb8aa3b, v91
	v_exp_f32_e32 v91, v91
	v_add_f32_e32 v88, 1.0, v88
	v_rcp_f32_e32 v88, v88
	v_add_f32_e32 v89, 1.0, v89
	v_rcp_f32_e32 v89, v89
	v_add_f32_e32 v90, 1.0, v90
	v_rcp_f32_e32 v90, v90
	v_add_f32_e32 v91, 1.0, v91
	v_rcp_f32_e32 v91, v91
	v_sub_f32_e32 v100, 1.0, v96
	v_fma_f32 v88, v88, v100, v96
	v_sub_f32_e32 v96, 1.0, v97
	v_fma_f32 v89, v89, v96, v97
	v_sub_f32_e32 v96, 1.0, v98
	v_fma_f32 v90, v90, v96, v98
	v_sub_f32_e32 v96, 1.0, v99
	v_fmac_f32_e32 v99, v91, v96
	v_log_f32_e32 v88, v88
	v_log_f32_e32 v89, v89
	v_log_f32_e32 v90, v90
	v_log_f32_e32 v91, v99
.LBB0_198:
	s_or_b64 exec, exec, s[8:9]
	s_andn2_saveexec_b64 s[2:3], s[2:3]
	s_cbranch_execnz .LBB0_202
	s_branch .LBB0_203

.LBB0_203:
	s_or_b64 exec, exec, s[2:3]
	v_add_u32_e32 v96, 32, v128
	v_ashrrev_i32_e32 v97, 31, v96
	v_cvt_pk_bf16_f32 v100, v88, v89
	v_lshl_add_u64 v[88:89], v[120:121], 0, v[96:97]
	v_lshlrev_b64 v[88:89], 12, v[88:89]
	v_cvt_pk_bf16_f32 v99, v94, v95
	v_cvt_pk_bf16_f32 v98, v92, v93
	v_cvt_pk_bf16_f32 v101, v90, v91
	v_lshl_add_u64 v[88:89], s[86:87], 0, v[88:89]
	v_permlane16_swap_b32_e32 v98, v100
	v_permlane16_swap_b32_e32 v99, v101
	v_lshl_add_u64 v[88:89], v[88:89], 0, v[176:177]
	global_store_dwordx4 v[88:89], v[98:101], off
	s_and_saveexec_b64 s[2:3], s[48:49]
	s_xor_b64 s[2:3], exec, s[2:3]
	s_cbranch_execz .LBB0_211
	v_cmp_ne_u32_e32 vcc, 3, v126
	s_and_saveexec_b64 s[8:9], vcc
	s_cbranch_execz .LBB0_206
	v_and_b32_e32 v88, 0xfffff800, v123
	v_add_u32_e32 v88, 0xfffff800, v88
	v_ashrrev_i32_e32 v89, 31, v88
	v_lshl_add_u64 v[88:89], v[88:89], 2, s[90:91]
	v_lshlrev_b32_e32 v90, 2, v122
	v_mov_b32_e32 v91, v177
	v_lshl_add_u64 v[88:89], v[88:89], 0, v[90:91]
	v_mov_b64_e32 v[88:89], v[152:153]
	v_mov_b64_e32 v[90:91], v[154:155]
	v_mul_f32_e32 v84, 0xbfb8aa3b, v84
	v_exp_f32_e32 v84, v84
	v_mul_f32_e32 v85, 0xbfb8aa3b, v85
	v_exp_f32_e32 v85, v85
	v_mul_f32_e32 v86, 0xbfb8aa3b, v86
	v_exp_f32_e32 v86, v86
	v_mul_f32_e32 v87, 0xbfb8aa3b, v87
	v_exp_f32_e32 v87, v87
	v_add_f32_e32 v84, 1.0, v84
	v_rcp_f32_e32 v84, v84
	v_add_f32_e32 v85, 1.0, v85
	v_rcp_f32_e32 v85, v85
	v_add_f32_e32 v86, 1.0, v86
	v_rcp_f32_e32 v86, v86
	v_add_f32_e32 v87, 1.0, v87
	v_rcp_f32_e32 v87, v87
	v_sub_f32_e32 v92, 1.0, v88
	v_fma_f32 v84, v84, v92, v88
	v_sub_f32_e32 v88, 1.0, v89
	v_fma_f32 v85, v85, v88, v89
	v_sub_f32_e32 v88, 1.0, v90
	v_fma_f32 v86, v86, v88, v90
	v_sub_f32_e32 v88, 1.0, v91
	v_fmac_f32_e32 v91, v87, v88
	v_log_f32_e32 v84, v84
	v_log_f32_e32 v85, v85
	v_log_f32_e32 v86, v86
	v_log_f32_e32 v87, v91
.LBB0_206:
	s_or_b64 exec, exec, s[8:9]
	s_andn2_saveexec_b64 s[2:3], s[2:3]
	s_cbranch_execnz .LBB0_212

.LBB0_208:
	v_cmp_ne_u32_e32 vcc, 3, v127
	s_and_saveexec_b64 s[8:9], vcc
	s_cbranch_execz .LBB0_210
	v_and_b32_e32 v88, 0xfffff800, v125
	v_add_u32_e32 v88, 0xfffff800, v88
	v_ashrrev_i32_e32 v89, 31, v88
	v_lshl_add_u64 v[88:89], v[88:89], 2, s[90:91]
	v_lshlrev_b32_e32 v90, 2, v124
	v_mov_b32_e32 v91, v177
	v_lshl_add_u64 v[88:89], v[88:89], 0, v[90:91]
	v_mov_b64_e32 v[88:89], v[156:157]
	v_mov_b64_e32 v[90:91], v[158:159]
	v_mul_f32_e32 v80, 0xbfb8aa3b, v80
	v_exp_f32_e32 v80, v80
	v_mul_f32_e32 v81, 0xbfb8aa3b, v81
	v_exp_f32_e32 v81, v81
	v_mul_f32_e32 v82, 0xbfb8aa3b, v82
	v_exp_f32_e32 v82, v82
	v_mul_f32_e32 v83, 0xbfb8aa3b, v83
	v_exp_f32_e32 v83, v83
	v_add_f32_e32 v80, 1.0, v80
	v_rcp_f32_e32 v80, v80
	v_add_f32_e32 v81, 1.0, v81
	v_rcp_f32_e32 v81, v81
	v_add_f32_e32 v82, 1.0, v82
	v_rcp_f32_e32 v82, v82
	v_add_f32_e32 v83, 1.0, v83
	v_rcp_f32_e32 v83, v83
	v_sub_f32_e32 v92, 1.0, v88
	v_fma_f32 v80, v80, v92, v88
	v_sub_f32_e32 v88, 1.0, v89
	v_fma_f32 v81, v81, v88, v89
	v_sub_f32_e32 v88, 1.0, v90
	v_fma_f32 v82, v82, v88, v90
	v_sub_f32_e32 v88, 1.0, v91
	v_fmac_f32_e32 v91, v83, v88
	v_log_f32_e32 v80, v80
	v_log_f32_e32 v81, v81
	v_log_f32_e32 v82, v82
	v_log_f32_e32 v83, v91
.LBB0_210:
	s_or_b64 exec, exec, s[8:9]
	s_andn2_saveexec_b64 s[2:3], s[2:3]
	s_cbranch_execnz .LBB0_214
	s_branch .LBB0_215

.LBB0_215:
	s_or_b64 exec, exec, s[2:3]
	v_cvt_pk_bf16_f32 v88, v80, v81
	v_lshl_add_u64 v[80:81], v[112:113], 0, v[96:97]
	v_lshlrev_b64 v[80:81], 12, v[80:81]
	v_cvt_pk_bf16_f32 v87, v86, v87
	v_cvt_pk_bf16_f32 v86, v84, v85
	v_cvt_pk_bf16_f32 v89, v82, v83
	v_lshl_add_u64 v[80:81], s[86:87], 0, v[80:81]
	v_mov_b32_e32 v115, v177
	v_permlane16_swap_b32_e32 v86, v88
	v_permlane16_swap_b32_e32 v87, v89
	v_lshl_add_u64 v[80:81], v[80:81], 0, v[114:115]
	global_store_dwordx4 v[80:81], v[86:89], off
	s_and_saveexec_b64 s[2:3], s[44:45]
	s_xor_b64 s[2:3], exec, s[2:3]
	s_cbranch_execz .LBB0_223
	v_cmp_ne_u32_e32 vcc, 3, v133
	s_and_saveexec_b64 s[8:9], vcc
	s_cbranch_execz .LBB0_218
	v_and_b32_e32 v80, 0xfffff800, v131
	v_add_u32_e32 v80, 0xfffff800, v80
	v_ashrrev_i32_e32 v81, 31, v80
	v_lshl_add_u64 v[80:81], v[80:81], 2, s[90:91]
	v_lshlrev_b32_e32 v82, 2, v130
	v_mov_b32_e32 v83, v177
	v_lshl_add_u64 v[80:81], v[80:81], 0, v[82:83]
	v_mov_b64_e32 v[80:81], v[144:145]
	v_mov_b64_e32 v[82:83], v[146:147]
	v_mul_f32_e32 v76, 0xbfb8aa3b, v76
	v_exp_f32_e32 v76, v76
	v_mul_f32_e32 v77, 0xbfb8aa3b, v77
	v_exp_f32_e32 v77, v77
	v_mul_f32_e32 v78, 0xbfb8aa3b, v78
	v_exp_f32_e32 v78, v78
	v_mul_f32_e32 v79, 0xbfb8aa3b, v79
	v_exp_f32_e32 v79, v79
	v_add_f32_e32 v76, 1.0, v76
	v_rcp_f32_e32 v76, v76
	v_add_f32_e32 v77, 1.0, v77
	v_rcp_f32_e32 v77, v77
	v_add_f32_e32 v78, 1.0, v78
	v_rcp_f32_e32 v78, v78
	v_add_f32_e32 v79, 1.0, v79
	v_rcp_f32_e32 v79, v79
	v_sub_f32_e32 v84, 1.0, v80
	v_fma_f32 v76, v76, v84, v80
	v_sub_f32_e32 v80, 1.0, v81
	v_fma_f32 v77, v77, v80, v81
	v_sub_f32_e32 v80, 1.0, v82
	v_fma_f32 v78, v78, v80, v82
	v_sub_f32_e32 v80, 1.0, v83
	v_fmac_f32_e32 v83, v79, v80
	v_log_f32_e32 v76, v76
	v_log_f32_e32 v77, v77
	v_log_f32_e32 v78, v78
	v_log_f32_e32 v79, v83
.LBB0_218:
	s_or_b64 exec, exec, s[8:9]
	s_andn2_saveexec_b64 s[2:3], s[2:3]
	s_cbranch_execnz .LBB0_224

.LBB0_220:
	v_cmp_ne_u32_e32 vcc, 3, v135
	s_and_saveexec_b64 s[8:9], vcc
	s_cbranch_execz .LBB0_222
	v_and_b32_e32 v80, 0xfffff800, v134
	v_add_u32_e32 v80, 0xfffff800, v80
	v_ashrrev_i32_e32 v81, 31, v80
	v_lshl_add_u64 v[80:81], v[80:81], 2, s[90:91]
	v_lshlrev_b32_e32 v82, 2, v132
	v_mov_b32_e32 v83, v177
	v_lshl_add_u64 v[80:81], v[80:81], 0, v[82:83]
	v_mov_b64_e32 v[80:81], v[148:149]
	v_mov_b64_e32 v[82:83], v[150:151]
	v_mul_f32_e32 v72, 0xbfb8aa3b, v72
	v_exp_f32_e32 v72, v72
	v_mul_f32_e32 v73, 0xbfb8aa3b, v73
	v_exp_f32_e32 v73, v73
	v_mul_f32_e32 v74, 0xbfb8aa3b, v74
	v_exp_f32_e32 v74, v74
	v_mul_f32_e32 v75, 0xbfb8aa3b, v75
	v_exp_f32_e32 v75, v75
	v_add_f32_e32 v72, 1.0, v72
	v_rcp_f32_e32 v72, v72
	v_add_f32_e32 v73, 1.0, v73
	v_rcp_f32_e32 v73, v73
	v_add_f32_e32 v74, 1.0, v74
	v_rcp_f32_e32 v74, v74
	v_add_f32_e32 v75, 1.0, v75
	v_rcp_f32_e32 v75, v75
	v_sub_f32_e32 v84, 1.0, v80
	v_fma_f32 v72, v72, v84, v80
	v_sub_f32_e32 v80, 1.0, v81
	v_fma_f32 v73, v73, v80, v81
	v_sub_f32_e32 v80, 1.0, v82
	v_fma_f32 v74, v74, v80, v82
	v_sub_f32_e32 v80, 1.0, v83
	v_fmac_f32_e32 v83, v75, v80
	v_log_f32_e32 v72, v72
	v_log_f32_e32 v73, v73
	v_log_f32_e32 v74, v74
	v_log_f32_e32 v75, v83
.LBB0_222:
	s_or_b64 exec, exec, s[8:9]
	s_andn2_saveexec_b64 s[2:3], s[2:3]
	s_cbranch_execnz .LBB0_226
	s_branch .LBB0_227

.LBB0_227:
	s_or_b64 exec, exec, s[2:3]
	v_add_u32_e32 v80, 48, v128
	v_ashrrev_i32_e32 v81, 31, v80
	v_cvt_pk_bf16_f32 v84, v72, v73
	v_lshl_add_u64 v[72:73], v[120:121], 0, v[80:81]
	v_lshlrev_b64 v[72:73], 12, v[72:73]
	v_cvt_pk_bf16_f32 v83, v78, v79
	v_cvt_pk_bf16_f32 v82, v76, v77
	v_cvt_pk_bf16_f32 v85, v74, v75
	v_lshl_add_u64 v[72:73], s[86:87], 0, v[72:73]
	v_permlane16_swap_b32_e32 v82, v84
	v_permlane16_swap_b32_e32 v83, v85
	v_lshl_add_u64 v[72:73], v[72:73], 0, v[176:177]
	global_store_dwordx4 v[72:73], v[82:85], off
	s_and_saveexec_b64 s[2:3], s[48:49]
	s_xor_b64 s[2:3], exec, s[2:3]
	s_cbranch_execz .LBB0_235
	v_cmp_ne_u32_e32 vcc, 3, v126
	s_and_saveexec_b64 s[8:9], vcc
	s_cbranch_execz .LBB0_230
	v_and_b32_e32 v72, 0xfffff800, v123
	v_add_u32_e32 v72, 0xfffff800, v72
	v_ashrrev_i32_e32 v73, 31, v72
	v_lshl_add_u64 v[72:73], v[72:73], 2, s[90:91]
	v_lshlrev_b32_e32 v74, 2, v122
	v_mov_b32_e32 v75, v177
	v_lshl_add_u64 v[72:73], v[72:73], 0, v[74:75]
	v_mov_b64_e32 v[72:73], v[152:153]
	v_mov_b64_e32 v[74:75], v[154:155]
	v_mul_f32_e32 v68, 0xbfb8aa3b, v68
	v_exp_f32_e32 v68, v68
	v_mul_f32_e32 v69, 0xbfb8aa3b, v69
	v_exp_f32_e32 v69, v69
	v_mul_f32_e32 v70, 0xbfb8aa3b, v70
	v_exp_f32_e32 v70, v70
	v_mul_f32_e32 v71, 0xbfb8aa3b, v71
	v_exp_f32_e32 v71, v71
	v_add_f32_e32 v68, 1.0, v68
	v_rcp_f32_e32 v68, v68
	v_add_f32_e32 v69, 1.0, v69
	v_rcp_f32_e32 v69, v69
	v_add_f32_e32 v70, 1.0, v70
	v_rcp_f32_e32 v70, v70
	v_add_f32_e32 v71, 1.0, v71
	v_rcp_f32_e32 v71, v71
	v_sub_f32_e32 v76, 1.0, v72
	v_fma_f32 v68, v68, v76, v72
	v_sub_f32_e32 v72, 1.0, v73
	v_fma_f32 v69, v69, v72, v73
	v_sub_f32_e32 v72, 1.0, v74
	v_fma_f32 v70, v70, v72, v74
	v_sub_f32_e32 v72, 1.0, v75
	v_fmac_f32_e32 v75, v71, v72
	v_log_f32_e32 v68, v68
	v_log_f32_e32 v69, v69
	v_log_f32_e32 v70, v70
	v_log_f32_e32 v71, v75
.LBB0_230:
	s_or_b64 exec, exec, s[8:9]
	s_andn2_saveexec_b64 s[2:3], s[2:3]
	s_cbranch_execnz .LBB0_236

.LBB0_232:
	v_cmp_ne_u32_e32 vcc, 3, v127
	s_and_saveexec_b64 s[8:9], vcc
	s_cbranch_execz .LBB0_234
	v_and_b32_e32 v72, 0xfffff800, v125
	v_add_u32_e32 v72, 0xfffff800, v72
	v_ashrrev_i32_e32 v73, 31, v72
	v_lshl_add_u64 v[72:73], v[72:73], 2, s[90:91]
	v_lshlrev_b32_e32 v74, 2, v124
	v_mov_b32_e32 v75, v177
	v_lshl_add_u64 v[72:73], v[72:73], 0, v[74:75]
	v_mov_b64_e32 v[72:73], v[156:157]
	v_mov_b64_e32 v[74:75], v[158:159]
	v_mul_f32_e32 v64, 0xbfb8aa3b, v64
	v_exp_f32_e32 v64, v64
	v_mul_f32_e32 v65, 0xbfb8aa3b, v65
	v_exp_f32_e32 v65, v65
	v_mul_f32_e32 v66, 0xbfb8aa3b, v66
	v_exp_f32_e32 v66, v66
	v_mul_f32_e32 v67, 0xbfb8aa3b, v67
	v_exp_f32_e32 v67, v67
	v_add_f32_e32 v64, 1.0, v64
	v_rcp_f32_e32 v64, v64
	v_add_f32_e32 v65, 1.0, v65
	v_rcp_f32_e32 v65, v65
	v_add_f32_e32 v66, 1.0, v66
	v_rcp_f32_e32 v66, v66
	v_add_f32_e32 v67, 1.0, v67
	v_rcp_f32_e32 v67, v67
	v_sub_f32_e32 v76, 1.0, v72
	v_fma_f32 v64, v64, v76, v72
	v_sub_f32_e32 v72, 1.0, v73
	v_fma_f32 v65, v65, v72, v73
	v_sub_f32_e32 v72, 1.0, v74
	v_fma_f32 v66, v66, v72, v74
	v_sub_f32_e32 v72, 1.0, v75
	v_fmac_f32_e32 v75, v67, v72
	v_log_f32_e32 v64, v64
	v_log_f32_e32 v65, v65
	v_log_f32_e32 v66, v66
	v_log_f32_e32 v67, v75
.LBB0_234:
	s_or_b64 exec, exec, s[8:9]
	s_andn2_saveexec_b64 s[2:3], s[2:3]
	s_cbranch_execnz .LBB0_238
	s_branch .LBB0_239

.LBB0_239:
	s_or_b64 exec, exec, s[2:3]
	v_cvt_pk_bf16_f32 v72, v64, v65
	v_lshl_add_u64 v[64:65], v[112:113], 0, v[80:81]
	v_lshlrev_b64 v[64:65], 12, v[64:65]
	v_cvt_pk_bf16_f32 v71, v70, v71
	v_cvt_pk_bf16_f32 v70, v68, v69
	v_cvt_pk_bf16_f32 v73, v66, v67
	v_lshl_add_u64 v[64:65], s[86:87], 0, v[64:65]
	v_mov_b32_e32 v115, v177
	v_permlane16_swap_b32_e32 v70, v72
	v_permlane16_swap_b32_e32 v71, v73
	v_lshl_add_u64 v[64:65], v[64:65], 0, v[114:115]
	global_store_dwordx4 v[64:65], v[70:73], off
	s_and_saveexec_b64 s[2:3], s[44:45]
	s_xor_b64 s[2:3], exec, s[2:3]
	s_cbranch_execz .LBB0_247
	v_cmp_ne_u32_e32 vcc, 3, v133
	s_and_saveexec_b64 s[8:9], vcc
	s_cbranch_execz .LBB0_242
	v_and_b32_e32 v64, 0xfffff800, v131
	v_add_u32_e32 v64, 0xfffff800, v64
	v_ashrrev_i32_e32 v65, 31, v64
	v_lshl_add_u64 v[64:65], v[64:65], 2, s[90:91]
	v_lshlrev_b32_e32 v66, 2, v130
	v_mov_b32_e32 v67, v177
	v_lshl_add_u64 v[64:65], v[64:65], 0, v[66:67]
	v_mov_b64_e32 v[64:65], v[144:145]
	v_mov_b64_e32 v[66:67], v[146:147]
	v_mul_f32_e32 v60, 0xbfb8aa3b, v60
	v_exp_f32_e32 v60, v60
	v_mul_f32_e32 v61, 0xbfb8aa3b, v61
	v_exp_f32_e32 v61, v61
	v_mul_f32_e32 v62, 0xbfb8aa3b, v62
	v_exp_f32_e32 v62, v62
	v_mul_f32_e32 v63, 0xbfb8aa3b, v63
	v_exp_f32_e32 v63, v63
	v_add_f32_e32 v60, 1.0, v60
	v_rcp_f32_e32 v60, v60
	v_add_f32_e32 v61, 1.0, v61
	v_rcp_f32_e32 v61, v61
	v_add_f32_e32 v62, 1.0, v62
	v_rcp_f32_e32 v62, v62
	v_add_f32_e32 v63, 1.0, v63
	v_rcp_f32_e32 v63, v63
	v_sub_f32_e32 v68, 1.0, v64
	v_fma_f32 v60, v60, v68, v64
	v_sub_f32_e32 v64, 1.0, v65
	v_fma_f32 v61, v61, v64, v65
	v_sub_f32_e32 v64, 1.0, v66
	v_fma_f32 v62, v62, v64, v66
	v_sub_f32_e32 v64, 1.0, v67
	v_fmac_f32_e32 v67, v63, v64
	v_log_f32_e32 v60, v60
	v_log_f32_e32 v61, v61
	v_log_f32_e32 v62, v62
	v_log_f32_e32 v63, v67
.LBB0_242:
	s_or_b64 exec, exec, s[8:9]
	s_andn2_saveexec_b64 s[2:3], s[2:3]
	s_cbranch_execnz .LBB0_248

.LBB0_244:
	v_cmp_ne_u32_e32 vcc, 3, v135
	s_and_saveexec_b64 s[8:9], vcc
	s_cbranch_execz .LBB0_246
	v_and_b32_e32 v64, 0xfffff800, v134
	v_add_u32_e32 v64, 0xfffff800, v64
	v_ashrrev_i32_e32 v65, 31, v64
	v_lshl_add_u64 v[64:65], v[64:65], 2, s[90:91]
	v_lshlrev_b32_e32 v66, 2, v132
	v_mov_b32_e32 v67, v177
	v_lshl_add_u64 v[64:65], v[64:65], 0, v[66:67]
	v_mov_b64_e32 v[64:65], v[148:149]
	v_mov_b64_e32 v[66:67], v[150:151]
	v_mul_f32_e32 v56, 0xbfb8aa3b, v56
	v_exp_f32_e32 v56, v56
	v_mul_f32_e32 v57, 0xbfb8aa3b, v57
	v_exp_f32_e32 v57, v57
	v_mul_f32_e32 v58, 0xbfb8aa3b, v58
	v_exp_f32_e32 v58, v58
	v_mul_f32_e32 v59, 0xbfb8aa3b, v59
	v_exp_f32_e32 v59, v59
	v_add_f32_e32 v56, 1.0, v56
	v_rcp_f32_e32 v56, v56
	v_add_f32_e32 v57, 1.0, v57
	v_rcp_f32_e32 v57, v57
	v_add_f32_e32 v58, 1.0, v58
	v_rcp_f32_e32 v58, v58
	v_add_f32_e32 v59, 1.0, v59
	v_rcp_f32_e32 v59, v59
	v_sub_f32_e32 v68, 1.0, v64
	v_fma_f32 v56, v56, v68, v64
	v_sub_f32_e32 v64, 1.0, v65
	v_fma_f32 v57, v57, v64, v65
	v_sub_f32_e32 v64, 1.0, v66
	v_fma_f32 v58, v58, v64, v66
	v_sub_f32_e32 v64, 1.0, v67
	v_fmac_f32_e32 v67, v59, v64
	v_log_f32_e32 v56, v56
	v_log_f32_e32 v57, v57
	v_log_f32_e32 v58, v58
	v_log_f32_e32 v59, v67
.LBB0_246:
	s_or_b64 exec, exec, s[8:9]
	s_andn2_saveexec_b64 s[2:3], s[2:3]
	s_cbranch_execnz .LBB0_250
	s_branch .LBB0_251

.LBB0_251:
	s_or_b64 exec, exec, s[2:3]
	v_add_u32_e32 v64, 64, v128
	v_ashrrev_i32_e32 v65, 31, v64
	v_cvt_pk_bf16_f32 v68, v56, v57
	v_lshl_add_u64 v[56:57], v[120:121], 0, v[64:65]
	v_lshlrev_b64 v[56:57], 12, v[56:57]
	v_cvt_pk_bf16_f32 v67, v62, v63
	v_cvt_pk_bf16_f32 v66, v60, v61
	v_cvt_pk_bf16_f32 v69, v58, v59
	v_lshl_add_u64 v[56:57], s[86:87], 0, v[56:57]
	v_permlane16_swap_b32_e32 v66, v68
	v_permlane16_swap_b32_e32 v67, v69
	v_lshl_add_u64 v[56:57], v[56:57], 0, v[176:177]
	global_store_dwordx4 v[56:57], v[66:69], off
	s_and_saveexec_b64 s[2:3], s[48:49]
	s_xor_b64 s[2:3], exec, s[2:3]
	s_cbranch_execz .LBB0_259
	v_cmp_ne_u32_e32 vcc, 3, v126
	s_and_saveexec_b64 s[8:9], vcc
	s_cbranch_execz .LBB0_254
	v_and_b32_e32 v56, 0xfffff800, v123
	v_add_u32_e32 v56, 0xfffff800, v56
	v_ashrrev_i32_e32 v57, 31, v56
	v_lshl_add_u64 v[56:57], v[56:57], 2, s[90:91]
	v_lshlrev_b32_e32 v58, 2, v122
	v_mov_b32_e32 v59, v177
	v_lshl_add_u64 v[56:57], v[56:57], 0, v[58:59]
	v_mov_b64_e32 v[56:57], v[152:153]
	v_mov_b64_e32 v[58:59], v[154:155]
	v_mul_f32_e32 v52, 0xbfb8aa3b, v52
	v_exp_f32_e32 v52, v52
	v_mul_f32_e32 v53, 0xbfb8aa3b, v53
	v_exp_f32_e32 v53, v53
	v_mul_f32_e32 v54, 0xbfb8aa3b, v54
	v_exp_f32_e32 v54, v54
	v_mul_f32_e32 v55, 0xbfb8aa3b, v55
	v_exp_f32_e32 v55, v55
	v_add_f32_e32 v52, 1.0, v52
	v_rcp_f32_e32 v52, v52
	v_add_f32_e32 v53, 1.0, v53
	v_rcp_f32_e32 v53, v53
	v_add_f32_e32 v54, 1.0, v54
	v_rcp_f32_e32 v54, v54
	v_add_f32_e32 v55, 1.0, v55
	v_rcp_f32_e32 v55, v55
	v_sub_f32_e32 v60, 1.0, v56
	v_fma_f32 v52, v52, v60, v56
	v_sub_f32_e32 v56, 1.0, v57
	v_fma_f32 v53, v53, v56, v57
	v_sub_f32_e32 v56, 1.0, v58
	v_fma_f32 v54, v54, v56, v58
	v_sub_f32_e32 v56, 1.0, v59
	v_fmac_f32_e32 v59, v55, v56
	v_log_f32_e32 v52, v52
	v_log_f32_e32 v53, v53
	v_log_f32_e32 v54, v54
	v_log_f32_e32 v55, v59
.LBB0_254:
	s_or_b64 exec, exec, s[8:9]
	s_andn2_saveexec_b64 s[2:3], s[2:3]
	s_cbranch_execnz .LBB0_260

.LBB0_256:
	v_cmp_ne_u32_e32 vcc, 3, v127
	s_and_saveexec_b64 s[8:9], vcc
	s_cbranch_execz .LBB0_258
	v_and_b32_e32 v56, 0xfffff800, v125
	v_add_u32_e32 v56, 0xfffff800, v56
	v_ashrrev_i32_e32 v57, 31, v56
	v_lshl_add_u64 v[56:57], v[56:57], 2, s[90:91]
	v_lshlrev_b32_e32 v58, 2, v124
	v_mov_b32_e32 v59, v177
	v_lshl_add_u64 v[56:57], v[56:57], 0, v[58:59]
	v_mov_b64_e32 v[56:57], v[156:157]
	v_mov_b64_e32 v[58:59], v[158:159]
	v_mul_f32_e32 v48, 0xbfb8aa3b, v48
	v_exp_f32_e32 v48, v48
	v_mul_f32_e32 v49, 0xbfb8aa3b, v49
	v_exp_f32_e32 v49, v49
	v_mul_f32_e32 v50, 0xbfb8aa3b, v50
	v_exp_f32_e32 v50, v50
	v_mul_f32_e32 v51, 0xbfb8aa3b, v51
	v_exp_f32_e32 v51, v51
	v_add_f32_e32 v48, 1.0, v48
	v_rcp_f32_e32 v48, v48
	v_add_f32_e32 v49, 1.0, v49
	v_rcp_f32_e32 v49, v49
	v_add_f32_e32 v50, 1.0, v50
	v_rcp_f32_e32 v50, v50
	v_add_f32_e32 v51, 1.0, v51
	v_rcp_f32_e32 v51, v51
	v_sub_f32_e32 v60, 1.0, v56
	v_fma_f32 v48, v48, v60, v56
	v_sub_f32_e32 v56, 1.0, v57
	v_fma_f32 v49, v49, v56, v57
	v_sub_f32_e32 v56, 1.0, v58
	v_fma_f32 v50, v50, v56, v58
	v_sub_f32_e32 v56, 1.0, v59
	v_fmac_f32_e32 v59, v51, v56
	v_log_f32_e32 v48, v48
	v_log_f32_e32 v49, v49
	v_log_f32_e32 v50, v50
	v_log_f32_e32 v51, v59
.LBB0_258:
	s_or_b64 exec, exec, s[8:9]
	s_andn2_saveexec_b64 s[2:3], s[2:3]
	s_cbranch_execnz .LBB0_262
	s_branch .LBB0_263

.LBB0_263:
	s_or_b64 exec, exec, s[2:3]
	v_cvt_pk_bf16_f32 v56, v48, v49
	v_lshl_add_u64 v[48:49], v[112:113], 0, v[64:65]
	v_lshlrev_b64 v[48:49], 12, v[48:49]
	v_cvt_pk_bf16_f32 v55, v54, v55
	v_cvt_pk_bf16_f32 v54, v52, v53
	v_cvt_pk_bf16_f32 v57, v50, v51
	v_lshl_add_u64 v[48:49], s[86:87], 0, v[48:49]
	v_mov_b32_e32 v115, v177
	v_permlane16_swap_b32_e32 v54, v56
	v_permlane16_swap_b32_e32 v55, v57
	v_lshl_add_u64 v[48:49], v[48:49], 0, v[114:115]
	global_store_dwordx4 v[48:49], v[54:57], off
	s_and_saveexec_b64 s[2:3], s[44:45]
	s_xor_b64 s[2:3], exec, s[2:3]
	s_cbranch_execz .LBB0_271
	v_cmp_ne_u32_e32 vcc, 3, v133
	s_and_saveexec_b64 s[8:9], vcc
	s_cbranch_execz .LBB0_266
	v_and_b32_e32 v48, 0xfffff800, v131
	v_add_u32_e32 v48, 0xfffff800, v48
	v_ashrrev_i32_e32 v49, 31, v48
	v_lshl_add_u64 v[48:49], v[48:49], 2, s[90:91]
	v_lshlrev_b32_e32 v50, 2, v130
	v_mov_b32_e32 v51, v177
	v_lshl_add_u64 v[48:49], v[48:49], 0, v[50:51]
	v_mov_b64_e32 v[48:49], v[144:145]
	v_mov_b64_e32 v[50:51], v[146:147]
	v_mul_f32_e32 v44, 0xbfb8aa3b, v44
	v_exp_f32_e32 v44, v44
	v_mul_f32_e32 v45, 0xbfb8aa3b, v45
	v_exp_f32_e32 v45, v45
	v_mul_f32_e32 v46, 0xbfb8aa3b, v46
	v_exp_f32_e32 v46, v46
	v_mul_f32_e32 v47, 0xbfb8aa3b, v47
	v_exp_f32_e32 v47, v47
	v_add_f32_e32 v44, 1.0, v44
	v_rcp_f32_e32 v44, v44
	v_add_f32_e32 v45, 1.0, v45
	v_rcp_f32_e32 v45, v45
	v_add_f32_e32 v46, 1.0, v46
	v_rcp_f32_e32 v46, v46
	v_add_f32_e32 v47, 1.0, v47
	v_rcp_f32_e32 v47, v47
	v_sub_f32_e32 v52, 1.0, v48
	v_fma_f32 v44, v44, v52, v48
	v_sub_f32_e32 v48, 1.0, v49
	v_fma_f32 v45, v45, v48, v49
	v_sub_f32_e32 v48, 1.0, v50
	v_fma_f32 v46, v46, v48, v50
	v_sub_f32_e32 v48, 1.0, v51
	v_fmac_f32_e32 v51, v47, v48
	v_log_f32_e32 v44, v44
	v_log_f32_e32 v45, v45
	v_log_f32_e32 v46, v46
	v_log_f32_e32 v47, v51
.LBB0_266:
	s_or_b64 exec, exec, s[8:9]
	s_andn2_saveexec_b64 s[2:3], s[2:3]
	s_cbranch_execnz .LBB0_272

.LBB0_268:
	v_cmp_ne_u32_e32 vcc, 3, v135
	s_and_saveexec_b64 s[8:9], vcc
	s_cbranch_execz .LBB0_270
	v_and_b32_e32 v48, 0xfffff800, v134
	v_add_u32_e32 v48, 0xfffff800, v48
	v_ashrrev_i32_e32 v49, 31, v48
	v_lshl_add_u64 v[48:49], v[48:49], 2, s[90:91]
	v_lshlrev_b32_e32 v50, 2, v132
	v_mov_b32_e32 v51, v177
	v_lshl_add_u64 v[48:49], v[48:49], 0, v[50:51]
	v_mov_b64_e32 v[48:49], v[148:149]
	v_mov_b64_e32 v[50:51], v[150:151]
	v_mul_f32_e32 v40, 0xbfb8aa3b, v40
	v_exp_f32_e32 v40, v40
	v_mul_f32_e32 v41, 0xbfb8aa3b, v41
	v_exp_f32_e32 v41, v41
	v_mul_f32_e32 v42, 0xbfb8aa3b, v42
	v_exp_f32_e32 v42, v42
	v_mul_f32_e32 v43, 0xbfb8aa3b, v43
	v_exp_f32_e32 v43, v43
	v_add_f32_e32 v40, 1.0, v40
	v_rcp_f32_e32 v40, v40
	v_add_f32_e32 v41, 1.0, v41
	v_rcp_f32_e32 v41, v41
	v_add_f32_e32 v42, 1.0, v42
	v_rcp_f32_e32 v42, v42
	v_add_f32_e32 v43, 1.0, v43
	v_rcp_f32_e32 v43, v43
	v_sub_f32_e32 v52, 1.0, v48
	v_fma_f32 v40, v40, v52, v48
	v_sub_f32_e32 v48, 1.0, v49
	v_fma_f32 v41, v41, v48, v49
	v_sub_f32_e32 v48, 1.0, v50
	v_fma_f32 v42, v42, v48, v50
	v_sub_f32_e32 v48, 1.0, v51
	v_fmac_f32_e32 v51, v43, v48
	v_log_f32_e32 v40, v40
	v_log_f32_e32 v41, v41
	v_log_f32_e32 v42, v42
	v_log_f32_e32 v43, v51
.LBB0_270:
	s_or_b64 exec, exec, s[8:9]
	s_andn2_saveexec_b64 s[2:3], s[2:3]
	s_cbranch_execnz .LBB0_274
	s_branch .LBB0_275

.LBB0_275:
	s_or_b64 exec, exec, s[2:3]
	v_add_u32_e32 v48, 0x50, v128
	v_ashrrev_i32_e32 v49, 31, v48
	v_cvt_pk_bf16_f32 v52, v40, v41
	v_lshl_add_u64 v[40:41], v[120:121], 0, v[48:49]
	v_lshlrev_b64 v[40:41], 12, v[40:41]
	v_cvt_pk_bf16_f32 v51, v46, v47
	v_cvt_pk_bf16_f32 v50, v44, v45
	v_cvt_pk_bf16_f32 v53, v42, v43
	v_lshl_add_u64 v[40:41], s[86:87], 0, v[40:41]
	v_permlane16_swap_b32_e32 v50, v52
	v_permlane16_swap_b32_e32 v51, v53
	v_lshl_add_u64 v[40:41], v[40:41], 0, v[176:177]
	global_store_dwordx4 v[40:41], v[50:53], off
	s_and_saveexec_b64 s[2:3], s[48:49]
	s_xor_b64 s[2:3], exec, s[2:3]
	s_cbranch_execz .LBB0_283
	v_cmp_ne_u32_e32 vcc, 3, v126
	s_and_saveexec_b64 s[8:9], vcc
	s_cbranch_execz .LBB0_278
	v_and_b32_e32 v40, 0xfffff800, v123
	v_add_u32_e32 v40, 0xfffff800, v40
	v_ashrrev_i32_e32 v41, 31, v40
	v_lshl_add_u64 v[40:41], v[40:41], 2, s[90:91]
	v_lshlrev_b32_e32 v42, 2, v122
	v_mov_b32_e32 v43, v177
	v_lshl_add_u64 v[40:41], v[40:41], 0, v[42:43]
	v_mov_b64_e32 v[40:41], v[152:153]
	v_mov_b64_e32 v[42:43], v[154:155]
	v_mul_f32_e32 v36, 0xbfb8aa3b, v36
	v_exp_f32_e32 v36, v36
	v_mul_f32_e32 v37, 0xbfb8aa3b, v37
	v_exp_f32_e32 v37, v37
	v_mul_f32_e32 v38, 0xbfb8aa3b, v38
	v_exp_f32_e32 v38, v38
	v_mul_f32_e32 v39, 0xbfb8aa3b, v39
	v_exp_f32_e32 v39, v39
	v_add_f32_e32 v36, 1.0, v36
	v_rcp_f32_e32 v36, v36
	v_add_f32_e32 v37, 1.0, v37
	v_rcp_f32_e32 v37, v37
	v_add_f32_e32 v38, 1.0, v38
	v_rcp_f32_e32 v38, v38
	v_add_f32_e32 v39, 1.0, v39
	v_rcp_f32_e32 v39, v39
	v_sub_f32_e32 v44, 1.0, v40
	v_fma_f32 v36, v36, v44, v40
	v_sub_f32_e32 v40, 1.0, v41
	v_fma_f32 v37, v37, v40, v41
	v_sub_f32_e32 v40, 1.0, v42
	v_fma_f32 v38, v38, v40, v42
	v_sub_f32_e32 v40, 1.0, v43
	v_fmac_f32_e32 v43, v39, v40
	v_log_f32_e32 v36, v36
	v_log_f32_e32 v37, v37
	v_log_f32_e32 v38, v38
	v_log_f32_e32 v39, v43
.LBB0_278:
	s_or_b64 exec, exec, s[8:9]
	s_andn2_saveexec_b64 s[2:3], s[2:3]
	s_cbranch_execnz .LBB0_284

.LBB0_280:
	v_cmp_ne_u32_e32 vcc, 3, v127
	s_and_saveexec_b64 s[8:9], vcc
	s_cbranch_execz .LBB0_282
	v_and_b32_e32 v40, 0xfffff800, v125
	v_add_u32_e32 v40, 0xfffff800, v40
	v_ashrrev_i32_e32 v41, 31, v40
	v_lshl_add_u64 v[40:41], v[40:41], 2, s[90:91]
	v_lshlrev_b32_e32 v42, 2, v124
	v_mov_b32_e32 v43, v177
	v_lshl_add_u64 v[40:41], v[40:41], 0, v[42:43]
	v_mov_b64_e32 v[40:41], v[156:157]
	v_mov_b64_e32 v[42:43], v[158:159]
	v_mul_f32_e32 v32, 0xbfb8aa3b, v32
	v_exp_f32_e32 v32, v32
	v_mul_f32_e32 v33, 0xbfb8aa3b, v33
	v_exp_f32_e32 v33, v33
	v_mul_f32_e32 v34, 0xbfb8aa3b, v34
	v_exp_f32_e32 v34, v34
	v_mul_f32_e32 v35, 0xbfb8aa3b, v35
	v_exp_f32_e32 v35, v35
	v_add_f32_e32 v32, 1.0, v32
	v_rcp_f32_e32 v32, v32
	v_add_f32_e32 v33, 1.0, v33
	v_rcp_f32_e32 v33, v33
	v_add_f32_e32 v34, 1.0, v34
	v_rcp_f32_e32 v34, v34
	v_add_f32_e32 v35, 1.0, v35
	v_rcp_f32_e32 v35, v35
	v_sub_f32_e32 v44, 1.0, v40
	v_fma_f32 v32, v32, v44, v40
	v_sub_f32_e32 v40, 1.0, v41
	v_fma_f32 v33, v33, v40, v41
	v_sub_f32_e32 v40, 1.0, v42
	v_fma_f32 v34, v34, v40, v42
	v_sub_f32_e32 v40, 1.0, v43
	v_fmac_f32_e32 v43, v35, v40
	v_log_f32_e32 v32, v32
	v_log_f32_e32 v33, v33
	v_log_f32_e32 v34, v34
	v_log_f32_e32 v35, v43
.LBB0_282:
	s_or_b64 exec, exec, s[8:9]
	s_andn2_saveexec_b64 s[2:3], s[2:3]
	s_cbranch_execnz .LBB0_286
	s_branch .LBB0_287

.LBB0_287:
	s_or_b64 exec, exec, s[2:3]
	v_cvt_pk_bf16_f32 v40, v32, v33
	v_lshl_add_u64 v[32:33], v[112:113], 0, v[48:49]
	v_lshlrev_b64 v[32:33], 12, v[32:33]
	v_cvt_pk_bf16_f32 v39, v38, v39
	v_cvt_pk_bf16_f32 v38, v36, v37
	v_cvt_pk_bf16_f32 v41, v34, v35
	v_lshl_add_u64 v[32:33], s[86:87], 0, v[32:33]
	v_mov_b32_e32 v115, v177
	v_permlane16_swap_b32_e32 v38, v40
	v_permlane16_swap_b32_e32 v39, v41
	v_lshl_add_u64 v[32:33], v[32:33], 0, v[114:115]
	global_store_dwordx4 v[32:33], v[38:41], off
	s_and_saveexec_b64 s[2:3], s[44:45]
	s_xor_b64 s[2:3], exec, s[2:3]
	s_cbranch_execz .LBB0_295
	v_cmp_ne_u32_e32 vcc, 3, v133
	s_and_saveexec_b64 s[8:9], vcc
	s_cbranch_execz .LBB0_290
	v_and_b32_e32 v32, 0xfffff800, v131
	v_add_u32_e32 v32, 0xfffff800, v32
	v_ashrrev_i32_e32 v33, 31, v32
	v_lshl_add_u64 v[32:33], v[32:33], 2, s[90:91]
	v_lshlrev_b32_e32 v34, 2, v130
	v_mov_b32_e32 v35, v177
	v_lshl_add_u64 v[32:33], v[32:33], 0, v[34:35]
	v_mov_b64_e32 v[32:33], v[144:145]
	v_mov_b64_e32 v[34:35], v[146:147]
	v_mul_f32_e32 v28, 0xbfb8aa3b, v28
	v_exp_f32_e32 v28, v28
	v_mul_f32_e32 v29, 0xbfb8aa3b, v29
	v_exp_f32_e32 v29, v29
	v_mul_f32_e32 v30, 0xbfb8aa3b, v30
	v_exp_f32_e32 v30, v30
	v_mul_f32_e32 v31, 0xbfb8aa3b, v31
	v_exp_f32_e32 v31, v31
	v_add_f32_e32 v28, 1.0, v28
	v_rcp_f32_e32 v28, v28
	v_add_f32_e32 v29, 1.0, v29
	v_rcp_f32_e32 v29, v29
	v_add_f32_e32 v30, 1.0, v30
	v_rcp_f32_e32 v30, v30
	v_add_f32_e32 v31, 1.0, v31
	v_rcp_f32_e32 v31, v31
	v_sub_f32_e32 v36, 1.0, v32
	v_fma_f32 v28, v28, v36, v32
	v_sub_f32_e32 v32, 1.0, v33
	v_fma_f32 v29, v29, v32, v33
	v_sub_f32_e32 v32, 1.0, v34
	v_fma_f32 v30, v30, v32, v34
	v_sub_f32_e32 v32, 1.0, v35
	v_fmac_f32_e32 v35, v31, v32
	v_log_f32_e32 v28, v28
	v_log_f32_e32 v29, v29
	v_log_f32_e32 v30, v30
	v_log_f32_e32 v31, v35
.LBB0_290:
	s_or_b64 exec, exec, s[8:9]
	s_andn2_saveexec_b64 s[2:3], s[2:3]
	s_cbranch_execnz .LBB0_296

.LBB0_292:
	v_cmp_ne_u32_e32 vcc, 3, v135
	s_and_saveexec_b64 s[8:9], vcc
	s_cbranch_execz .LBB0_294
	v_and_b32_e32 v32, 0xfffff800, v134
	v_add_u32_e32 v32, 0xfffff800, v32
	v_ashrrev_i32_e32 v33, 31, v32
	v_lshl_add_u64 v[32:33], v[32:33], 2, s[90:91]
	v_lshlrev_b32_e32 v34, 2, v132
	v_mov_b32_e32 v35, v177
	v_lshl_add_u64 v[32:33], v[32:33], 0, v[34:35]
	v_mov_b64_e32 v[32:33], v[148:149]
	v_mov_b64_e32 v[34:35], v[150:151]
	v_mul_f32_e32 v24, 0xbfb8aa3b, v24
	v_exp_f32_e32 v24, v24
	v_mul_f32_e32 v25, 0xbfb8aa3b, v25
	v_exp_f32_e32 v25, v25
	v_mul_f32_e32 v26, 0xbfb8aa3b, v26
	v_exp_f32_e32 v26, v26
	v_mul_f32_e32 v27, 0xbfb8aa3b, v27
	v_exp_f32_e32 v27, v27
	v_add_f32_e32 v24, 1.0, v24
	v_rcp_f32_e32 v24, v24
	v_add_f32_e32 v25, 1.0, v25
	v_rcp_f32_e32 v25, v25
	v_add_f32_e32 v26, 1.0, v26
	v_rcp_f32_e32 v26, v26
	v_add_f32_e32 v27, 1.0, v27
	v_rcp_f32_e32 v27, v27
	v_sub_f32_e32 v36, 1.0, v32
	v_fma_f32 v24, v24, v36, v32
	v_sub_f32_e32 v32, 1.0, v33
	v_fma_f32 v25, v25, v32, v33
	v_sub_f32_e32 v32, 1.0, v34
	v_fma_f32 v26, v26, v32, v34
	v_sub_f32_e32 v32, 1.0, v35
	v_fmac_f32_e32 v35, v27, v32
	v_log_f32_e32 v24, v24
	v_log_f32_e32 v25, v25
	v_log_f32_e32 v26, v26
	v_log_f32_e32 v27, v35
.LBB0_294:
	s_or_b64 exec, exec, s[8:9]
	s_andn2_saveexec_b64 s[2:3], s[2:3]
	s_cbranch_execnz .LBB0_298
	s_branch .LBB0_299

.LBB0_299:
	s_or_b64 exec, exec, s[2:3]
	v_add_u32_e32 v32, 0x60, v128
	v_ashrrev_i32_e32 v33, 31, v32
	v_cvt_pk_bf16_f32 v36, v24, v25
	v_lshl_add_u64 v[24:25], v[120:121], 0, v[32:33]
	v_lshlrev_b64 v[24:25], 12, v[24:25]
	v_cvt_pk_bf16_f32 v35, v30, v31
	v_cvt_pk_bf16_f32 v34, v28, v29
	v_cvt_pk_bf16_f32 v37, v26, v27
	v_lshl_add_u64 v[24:25], s[86:87], 0, v[24:25]
	v_permlane16_swap_b32_e32 v34, v36
	v_permlane16_swap_b32_e32 v35, v37
	v_lshl_add_u64 v[24:25], v[24:25], 0, v[176:177]
	global_store_dwordx4 v[24:25], v[34:37], off
	s_and_saveexec_b64 s[2:3], s[48:49]
	s_xor_b64 s[2:3], exec, s[2:3]
	s_cbranch_execz .LBB0_307
	v_cmp_ne_u32_e32 vcc, 3, v126
	s_and_saveexec_b64 s[8:9], vcc
	s_cbranch_execz .LBB0_302
	v_and_b32_e32 v24, 0xfffff800, v123
	v_add_u32_e32 v24, 0xfffff800, v24
	v_ashrrev_i32_e32 v25, 31, v24
	v_lshl_add_u64 v[24:25], v[24:25], 2, s[90:91]
	v_lshlrev_b32_e32 v26, 2, v122
	v_mov_b32_e32 v27, v177
	v_lshl_add_u64 v[24:25], v[24:25], 0, v[26:27]
	v_mov_b64_e32 v[24:25], v[152:153]
	v_mov_b64_e32 v[26:27], v[154:155]
	v_mul_f32_e32 v20, 0xbfb8aa3b, v20
	v_exp_f32_e32 v20, v20
	v_mul_f32_e32 v21, 0xbfb8aa3b, v21
	v_exp_f32_e32 v21, v21
	v_mul_f32_e32 v22, 0xbfb8aa3b, v22
	v_exp_f32_e32 v22, v22
	v_mul_f32_e32 v23, 0xbfb8aa3b, v23
	v_exp_f32_e32 v23, v23
	v_add_f32_e32 v20, 1.0, v20
	v_rcp_f32_e32 v20, v20
	v_add_f32_e32 v21, 1.0, v21
	v_rcp_f32_e32 v21, v21
	v_add_f32_e32 v22, 1.0, v22
	v_rcp_f32_e32 v22, v22
	v_add_f32_e32 v23, 1.0, v23
	v_rcp_f32_e32 v23, v23
	v_sub_f32_e32 v28, 1.0, v24
	v_fma_f32 v20, v20, v28, v24
	v_sub_f32_e32 v24, 1.0, v25
	v_fma_f32 v21, v21, v24, v25
	v_sub_f32_e32 v24, 1.0, v26
	v_fma_f32 v22, v22, v24, v26
	v_sub_f32_e32 v24, 1.0, v27
	v_fmac_f32_e32 v27, v23, v24
	v_log_f32_e32 v20, v20
	v_log_f32_e32 v21, v21
	v_log_f32_e32 v22, v22
	v_log_f32_e32 v23, v27
.LBB0_302:
	s_or_b64 exec, exec, s[8:9]
	s_andn2_saveexec_b64 s[2:3], s[2:3]
	s_cbranch_execnz .LBB0_308

.LBB0_304:
	v_cmp_ne_u32_e32 vcc, 3, v127
	s_and_saveexec_b64 s[8:9], vcc
	s_cbranch_execz .LBB0_306
	v_and_b32_e32 v24, 0xfffff800, v125
	v_add_u32_e32 v24, 0xfffff800, v24
	v_ashrrev_i32_e32 v25, 31, v24
	v_lshl_add_u64 v[24:25], v[24:25], 2, s[90:91]
	v_lshlrev_b32_e32 v26, 2, v124
	v_mov_b32_e32 v27, v177
	v_lshl_add_u64 v[24:25], v[24:25], 0, v[26:27]
	v_mov_b64_e32 v[24:25], v[156:157]
	v_mov_b64_e32 v[26:27], v[158:159]
	v_mul_f32_e32 v16, 0xbfb8aa3b, v16
	v_exp_f32_e32 v16, v16
	v_mul_f32_e32 v17, 0xbfb8aa3b, v17
	v_exp_f32_e32 v17, v17
	v_mul_f32_e32 v18, 0xbfb8aa3b, v18
	v_exp_f32_e32 v18, v18
	v_mul_f32_e32 v19, 0xbfb8aa3b, v19
	v_exp_f32_e32 v19, v19
	v_add_f32_e32 v16, 1.0, v16
	v_rcp_f32_e32 v16, v16
	v_add_f32_e32 v17, 1.0, v17
	v_rcp_f32_e32 v17, v17
	v_add_f32_e32 v18, 1.0, v18
	v_rcp_f32_e32 v18, v18
	v_add_f32_e32 v19, 1.0, v19
	v_rcp_f32_e32 v19, v19
	v_sub_f32_e32 v28, 1.0, v24
	v_fma_f32 v16, v16, v28, v24
	v_sub_f32_e32 v24, 1.0, v25
	v_fma_f32 v17, v17, v24, v25
	v_sub_f32_e32 v24, 1.0, v26
	v_fma_f32 v18, v18, v24, v26
	v_sub_f32_e32 v24, 1.0, v27
	v_fmac_f32_e32 v27, v19, v24
	v_log_f32_e32 v16, v16
	v_log_f32_e32 v17, v17
	v_log_f32_e32 v18, v18
	v_log_f32_e32 v19, v27
.LBB0_306:
	s_or_b64 exec, exec, s[8:9]
	s_andn2_saveexec_b64 s[2:3], s[2:3]
	s_cbranch_execnz .LBB0_310
	s_branch .LBB0_311

.LBB0_311:
	s_or_b64 exec, exec, s[2:3]
	v_cvt_pk_bf16_f32 v24, v16, v17
	v_lshl_add_u64 v[16:17], v[112:113], 0, v[32:33]
	v_lshlrev_b64 v[16:17], 12, v[16:17]
	v_cvt_pk_bf16_f32 v23, v22, v23
	v_cvt_pk_bf16_f32 v22, v20, v21
	v_cvt_pk_bf16_f32 v25, v18, v19
	v_lshl_add_u64 v[16:17], s[86:87], 0, v[16:17]
	v_mov_b32_e32 v115, v177
	v_permlane16_swap_b32_e32 v22, v24
	v_permlane16_swap_b32_e32 v23, v25
	v_lshl_add_u64 v[16:17], v[16:17], 0, v[114:115]
	global_store_dwordx4 v[16:17], v[22:25], off
	s_and_saveexec_b64 s[2:3], s[44:45]
	s_xor_b64 s[2:3], exec, s[2:3]
	s_cbranch_execz .LBB0_319
	v_cmp_ne_u32_e32 vcc, 3, v133
	s_and_saveexec_b64 s[8:9], vcc
	s_cbranch_execz .LBB0_314
	v_and_b32_e32 v16, 0xfffff800, v131
	v_add_u32_e32 v16, 0xfffff800, v16
	v_ashrrev_i32_e32 v17, 31, v16
	v_lshl_add_u64 v[16:17], v[16:17], 2, s[90:91]
	v_lshlrev_b32_e32 v18, 2, v130
	v_mov_b32_e32 v19, v177
	v_lshl_add_u64 v[16:17], v[16:17], 0, v[18:19]
	v_mov_b64_e32 v[16:17], v[144:145]
	v_mov_b64_e32 v[18:19], v[146:147]
	v_mul_f32_e32 v12, 0xbfb8aa3b, v12
	v_exp_f32_e32 v12, v12
	v_mul_f32_e32 v13, 0xbfb8aa3b, v13
	v_exp_f32_e32 v13, v13
	v_mul_f32_e32 v14, 0xbfb8aa3b, v14
	v_exp_f32_e32 v14, v14
	v_mul_f32_e32 v15, 0xbfb8aa3b, v15
	v_exp_f32_e32 v15, v15
	v_add_f32_e32 v12, 1.0, v12
	v_rcp_f32_e32 v12, v12
	v_add_f32_e32 v13, 1.0, v13
	v_rcp_f32_e32 v13, v13
	v_add_f32_e32 v14, 1.0, v14
	v_rcp_f32_e32 v14, v14
	v_add_f32_e32 v15, 1.0, v15
	v_rcp_f32_e32 v15, v15
	v_sub_f32_e32 v20, 1.0, v16
	v_fma_f32 v12, v12, v20, v16
	v_sub_f32_e32 v16, 1.0, v17
	v_fma_f32 v13, v13, v16, v17
	v_sub_f32_e32 v16, 1.0, v18
	v_fma_f32 v14, v14, v16, v18
	v_sub_f32_e32 v16, 1.0, v19
	v_fmac_f32_e32 v19, v15, v16
	v_log_f32_e32 v12, v12
	v_log_f32_e32 v13, v13
	v_log_f32_e32 v14, v14
	v_log_f32_e32 v15, v19
.LBB0_314:
	s_or_b64 exec, exec, s[8:9]
	s_andn2_saveexec_b64 s[2:3], s[2:3]
	s_cbranch_execnz .LBB0_320

.LBB0_316:
	v_cmp_ne_u32_e32 vcc, 3, v135
	s_and_saveexec_b64 s[8:9], vcc
	s_cbranch_execz .LBB0_318
	v_and_b32_e32 v16, 0xfffff800, v134
	v_add_u32_e32 v16, 0xfffff800, v16
	v_ashrrev_i32_e32 v17, 31, v16
	v_lshl_add_u64 v[16:17], v[16:17], 2, s[90:91]
	v_lshlrev_b32_e32 v18, 2, v132
	v_mov_b32_e32 v19, v177
	v_lshl_add_u64 v[16:17], v[16:17], 0, v[18:19]
	v_mov_b64_e32 v[16:17], v[148:149]
	v_mov_b64_e32 v[18:19], v[150:151]
	v_mul_f32_e32 v8, 0xbfb8aa3b, v8
	v_exp_f32_e32 v8, v8
	v_mul_f32_e32 v9, 0xbfb8aa3b, v9
	v_exp_f32_e32 v9, v9
	v_mul_f32_e32 v10, 0xbfb8aa3b, v10
	v_exp_f32_e32 v10, v10
	v_mul_f32_e32 v11, 0xbfb8aa3b, v11
	v_exp_f32_e32 v11, v11
	v_add_f32_e32 v8, 1.0, v8
	v_rcp_f32_e32 v8, v8
	v_add_f32_e32 v9, 1.0, v9
	v_rcp_f32_e32 v9, v9
	v_add_f32_e32 v10, 1.0, v10
	v_rcp_f32_e32 v10, v10
	v_add_f32_e32 v11, 1.0, v11
	v_rcp_f32_e32 v11, v11
	v_sub_f32_e32 v20, 1.0, v16
	v_fma_f32 v8, v8, v20, v16
	v_sub_f32_e32 v16, 1.0, v17
	v_fma_f32 v9, v9, v16, v17
	v_sub_f32_e32 v16, 1.0, v18
	v_fma_f32 v10, v10, v16, v18
	v_sub_f32_e32 v16, 1.0, v19
	v_fmac_f32_e32 v19, v11, v16
	v_log_f32_e32 v8, v8
	v_log_f32_e32 v9, v9
	v_log_f32_e32 v10, v10
	v_log_f32_e32 v11, v19
.LBB0_318:
	s_or_b64 exec, exec, s[8:9]
	s_andn2_saveexec_b64 s[2:3], s[2:3]
	s_cbranch_execnz .LBB0_322
	s_branch .LBB0_323

.LBB0_323:
	s_or_b64 exec, exec, s[2:3]
	v_add_u32_e32 v16, 0x70, v128
	v_ashrrev_i32_e32 v17, 31, v16
	v_cvt_pk_bf16_f32 v20, v8, v9
	v_lshl_add_u64 v[8:9], v[120:121], 0, v[16:17]
	v_lshlrev_b64 v[8:9], 12, v[8:9]
	v_cvt_pk_bf16_f32 v19, v14, v15
	v_cvt_pk_bf16_f32 v18, v12, v13
	v_cvt_pk_bf16_f32 v21, v10, v11
	v_lshl_add_u64 v[8:9], s[86:87], 0, v[8:9]
	v_permlane16_swap_b32_e32 v18, v20
	v_permlane16_swap_b32_e32 v19, v21
	v_lshl_add_u64 v[8:9], v[8:9], 0, v[176:177]
	global_store_dwordx4 v[8:9], v[18:21], off
	s_and_saveexec_b64 s[2:3], s[48:49]
	s_xor_b64 s[2:3], exec, s[2:3]
	s_cbranch_execz .LBB0_331
	v_cmp_ne_u32_e32 vcc, 3, v126
	s_and_saveexec_b64 s[8:9], vcc
	s_cbranch_execz .LBB0_326
	v_and_b32_e32 v8, 0xfffff800, v123
	v_add_u32_e32 v8, 0xfffff800, v8
	v_ashrrev_i32_e32 v9, 31, v8
	v_lshl_add_u64 v[8:9], v[8:9], 2, s[90:91]
	v_lshlrev_b32_e32 v176, 2, v122
	v_lshl_add_u64 v[8:9], v[8:9], 0, v[176:177]
	v_mov_b64_e32 v[8:9], v[152:153]
	v_mov_b64_e32 v[10:11], v[154:155]
	v_mul_f32_e32 v4, 0xbfb8aa3b, v4
	v_exp_f32_e32 v4, v4
	v_mul_f32_e32 v5, 0xbfb8aa3b, v5
	v_exp_f32_e32 v5, v5
	v_mul_f32_e32 v6, 0xbfb8aa3b, v6
	v_exp_f32_e32 v6, v6
	v_mul_f32_e32 v7, 0xbfb8aa3b, v7
	v_exp_f32_e32 v7, v7
	v_add_f32_e32 v4, 1.0, v4
	v_rcp_f32_e32 v4, v4
	v_add_f32_e32 v5, 1.0, v5
	v_rcp_f32_e32 v5, v5
	v_add_f32_e32 v6, 1.0, v6
	v_rcp_f32_e32 v6, v6
	v_add_f32_e32 v7, 1.0, v7
	v_rcp_f32_e32 v7, v7
	v_sub_f32_e32 v12, 1.0, v8
	v_fma_f32 v4, v4, v12, v8
	v_sub_f32_e32 v8, 1.0, v9
	v_fma_f32 v5, v5, v8, v9
	v_sub_f32_e32 v8, 1.0, v10
	v_fma_f32 v6, v6, v8, v10
	v_sub_f32_e32 v8, 1.0, v11
	v_fmac_f32_e32 v11, v7, v8
	v_log_f32_e32 v4, v4
	v_log_f32_e32 v5, v5
	v_log_f32_e32 v6, v6
	v_log_f32_e32 v7, v11
.LBB0_326:
	s_or_b64 exec, exec, s[8:9]
	s_andn2_saveexec_b64 s[2:3], s[2:3]
	s_cbranch_execnz .LBB0_332

.LBB0_328:
	v_cmp_ne_u32_e32 vcc, 3, v127
	s_and_saveexec_b64 s[2:3], vcc
	s_cbranch_execz .LBB0_330
	v_and_b32_e32 v8, 0xfffff800, v125
	v_add_u32_e32 v8, 0xfffff800, v8
	v_ashrrev_i32_e32 v9, 31, v8
	v_lshl_add_u64 v[8:9], v[8:9], 2, s[90:91]
	v_lshlrev_b32_e32 v176, 2, v124
	v_lshl_add_u64 v[8:9], v[8:9], 0, v[176:177]
	v_mov_b64_e32 v[8:9], v[156:157]
	v_mov_b64_e32 v[10:11], v[158:159]
	v_mul_f32_e32 v0, 0xbfb8aa3b, v0
	v_exp_f32_e32 v0, v0
	v_mul_f32_e32 v1, 0xbfb8aa3b, v1
	v_exp_f32_e32 v1, v1
	v_mul_f32_e32 v2, 0xbfb8aa3b, v2
	v_exp_f32_e32 v2, v2
	v_mul_f32_e32 v3, 0xbfb8aa3b, v3
	v_exp_f32_e32 v3, v3
	v_add_f32_e32 v0, 1.0, v0
	v_rcp_f32_e32 v0, v0
	v_add_f32_e32 v1, 1.0, v1
	v_rcp_f32_e32 v1, v1
	v_add_f32_e32 v2, 1.0, v2
	v_rcp_f32_e32 v2, v2
	v_add_f32_e32 v3, 1.0, v3
	v_rcp_f32_e32 v3, v3
	v_sub_f32_e32 v12, 1.0, v8
	v_fma_f32 v0, v0, v12, v8
	v_sub_f32_e32 v8, 1.0, v9
	v_fma_f32 v1, v1, v8, v9
	v_sub_f32_e32 v8, 1.0, v10
	v_fma_f32 v2, v2, v8, v10
	v_sub_f32_e32 v8, 1.0, v11
	v_fmac_f32_e32 v11, v3, v8
	v_log_f32_e32 v0, v0
	v_log_f32_e32 v1, v1
	v_log_f32_e32 v2, v2
	v_log_f32_e32 v3, v11
.LBB0_330:
	s_or_b64 exec, exec, s[2:3]
	s_andn2_saveexec_b64 s[0:1], s[0:1]
	s_cbranch_execz .LBB0_122
	s_branch .LBB0_334

.LBB0_404:
	s_bitcmp1_b32 s24, 0
	s_cselect_b32 s20, 0, 0x5200
	v_add_u32_e32 v80, s20, v145
	ds_read_u16 v81, v80 offset:8320
	ds_read_u16 v82, v80
	ds_read_u16 v83, v80 offset:8576
	ds_read_u16 v84, v80 offset:8832
	ds_read_u16 v85, v80 offset:9088
	ds_read_u16 v86, v80 offset:768
	s_waitcnt lgkmcnt(0)
	v_lshlrev_b32_e32 v81, 16, v81
	ds_read_u16 v87, v80 offset:512
	ds_read_u16 v91, v80 offset:256
	v_add_f32_e32 v90, 0, v81
	v_lshlrev_b32_e32 v83, 16, v83
	v_lshlrev_b32_e32 v93, 16, v82
	v_exp_f32_e32 v82, v81
	v_add_f32_e32 v94, v90, v83
	v_lshlrev_b32_e32 v80, 16, v84
	v_add_f32_e32 v96, v94, v80
	v_exp_f32_e32 v84, v80
	v_lshlrev_b32_e32 v80, 16, v85
	s_waitcnt lgkmcnt(0)
	v_lshlrev_b32_e32 v95, 16, v87
	v_add_u32_e32 v81, s20, v146
	v_add_u32_e32 v85, s20, v166
	v_add_u32_e32 v87, s20, v168
	v_add_f32_e32 v101, v96, v80
	v_lshlrev_b32_e32 v97, 16, v86
	v_add_u32_e32 v86, s20, v167
	ds_read_u16 v88, v81 offset:8320
	ds_read_u16 v89, v85 offset:8576
	ds_read_u16 v92, v86 offset:8832
	ds_read_u16 v98, v87 offset:9088
	ds_read_u16 v99, v87 offset:768
	ds_read_u16 v100, v86 offset:512
	ds_read_u16 v87, v85 offset:256
	ds_read_u16 v81, v81
	v_exp_f32_e32 v85, v80
	s_waitcnt lgkmcnt(0)
	v_lshlrev_b32_e32 v80, 16, v88
	v_add_f32_e32 v103, v101, v80
	v_exp_f32_e32 v86, v80
	v_lshlrev_b32_e32 v80, 16, v89
	v_add_f32_e32 v105, v103, v80
	v_lshlrev_b32_e32 v104, 16, v87
	v_exp_f32_e32 v87, v80
	v_lshlrev_b32_e32 v80, 16, v92
	v_add_f32_e32 v106, v105, v80
	v_exp_f32_e32 v88, v80
	v_lshlrev_b32_e32 v80, 16, v98
	v_lshlrev_b32_e32 v102, 16, v81
	v_add_f32_e32 v81, v106, v80
	v_exp_f32_e32 v89, v80
	v_lshlrev_b32_e32 v98, 16, v99
	v_add_f32_dpp v80, v81, v81 quad_perm:[0,0,1,2] row_mask:0xf bank_mask:0xf bound_ctrl:1
	v_cndmask_b32_e64 v80, v80, v81, s[0:1]
	v_exp_f32_e32 v83, v83
	v_add_f32_dpp v92, v80, v80 quad_perm:[0,1,0,1] row_mask:0xf bank_mask:0xf bound_ctrl:1
	v_cndmask_b32_e64 v80, v80, v92, s[38:39]
	v_sub_f32_e32 v99, v80, v81
	v_add_f32_e32 v107, v81, v99
	v_add_f32_e32 v90, v90, v99
	v_mov_b32_dpp v80, v80 quad_perm:[3,3,3,3] row_mask:0xf bank_mask:0xf bound_ctrl:1
	v_mov_b32_dpp v81, v107 quad_perm:[1,1,1,1] row_mask:0xf bank_mask:0xf bound_ctrl:1
	v_sub_f32_e32 v90, v90, v81
	v_exp_f32_e32 v108, v90
	v_sub_f32_e32 v90, v80, v81
	v_exp_f32_e32 v90, v90
	v_mul_f32_e32 v93, v108, v93
	v_cvt_pk_bf16_f32 v93, v93, s0
	ds_write_b16 v147, v93 offset:41984
	v_add_f32_e32 v93, v94, v99
	v_sub_f32_e32 v93, v93, v81
	v_exp_f32_e32 v94, v93
	v_rcp_f32_e32 v92, v108
	v_lshlrev_b32_e32 v91, 16, v91
	v_pk_add_f32 v[82:83], v[82:83], 1.0 op_sel_hi:[1,0] neg_lo:[1,0] neg_hi:[1,0]
	v_rcp_f32_e32 v93, v94
	v_mul_f32_e32 v91, v94, v91
	v_cvt_pk_bf16_f32 v91, v91, s0
	v_pk_add_f32 v[84:85], v[84:85], 1.0 op_sel_hi:[1,0] neg_lo:[1,0] neg_hi:[1,0]
	v_pk_mul_f32 v[82:83], v[82:83], v[92:93]
	v_pk_add_f32 v[86:87], v[86:87], 1.0 op_sel_hi:[1,0] neg_lo:[1,0] neg_hi:[1,0]
	v_cvt_pk_bf16_f32 v92, v82, s0
	ds_write_b16 v147, v92 offset:50176
	ds_write_b16 v148, v91 offset:41984
	v_cvt_pk_bf16_f32 v91, v83, s0
	v_pk_mul_f32 v[82:83], v[90:91], v[82:83] op_sel_hi:[0,1]
	v_add_f32_e32 v92, v96, v99
	v_cvt_pk_bf16_f32 v82, v82, v83
	v_add_f32_e32 v83, v101, v99
	v_sub_f32_e32 v92, v92, v81
	v_sub_f32_e32 v83, v83, v81
	v_exp_f32_e32 v93, v92
	v_exp_f32_e32 v83, v83
	ds_write_b16 v148, v91 offset:50176
	v_lshlrev_b32_e32 v100, 16, v100
	v_rcp_f32_e32 v92, v93
	v_mul_f32_e32 v91, v93, v95
	v_rcp_f32_e32 v93, v83
	v_cvt_pk_bf16_f32 v91, v91, s0
	ds_write_b16 v149, v91 offset:41984
	v_mul_f32_e32 v83, v83, v97
	v_pk_mul_f32 v[84:85], v[84:85], v[92:93]
	v_cvt_pk_bf16_f32 v83, v83, s0
	v_cvt_pk_bf16_f32 v91, v84, s0
	ds_write_b16 v149, v91 offset:50176
	ds_write_b16 v150, v83 offset:41984
	v_add_f32_e32 v91, v103, v99
	v_sub_f32_e32 v91, v91, v81
	v_exp_f32_e32 v91, v91
	v_cvt_pk_bf16_f32 v83, v85, s0
	ds_write_b16 v150, v83 offset:50176
	v_pk_add_f32 v[88:89], v[88:89], 1.0 op_sel_hi:[1,0] neg_lo:[1,0] neg_hi:[1,0]
	v_pk_mul_f32 v[84:85], v[90:91], v[84:85] op_sel_hi:[0,1]
	v_cvt_pk_bf16_f32 v83, v84, v85
	v_add_f32_e32 v85, v105, v99
	v_sub_f32_e32 v85, v85, v81
	v_exp_f32_e32 v92, v85
	v_mul_f32_e32 v85, v91, v102
	v_cvt_pk_bf16_f32 v85, v85, s0
	v_rcp_f32_e32 v84, v91
	ds_write_b16 v151, v85 offset:41984
	v_rcp_f32_e32 v85, v92
	v_mul_f32_e32 v91, v92, v104
	v_cvt_pk_bf16_f32 v91, v91, s0
	v_pk_mul_f32 v[84:85], v[86:87], v[84:85]
	v_add_f32_e32 v87, v106, v99
	v_cvt_pk_bf16_f32 v86, v84, s0
	v_sub_f32_e32 v87, v87, v81
	ds_write_b16 v151, v86 offset:50176
	ds_write_b16 v152, v91 offset:41984
	v_cvt_pk_bf16_f32 v86, v85, s0
	v_pk_mul_f32 v[84:85], v[90:91], v[84:85] op_sel_hi:[0,1]
	v_exp_f32_e32 v87, v87
	v_cvt_pk_bf16_f32 v84, v84, v85
	v_sub_f32_e32 v85, v107, v81
	v_exp_f32_e32 v85, v85
	ds_write_b16 v152, v86 offset:50176
	v_rcp_f32_e32 v86, v87
	v_mul_f32_e32 v87, v87, v100
	v_cvt_pk_bf16_f32 v87, v87, s0
	ds_write_b16 v153, v87 offset:41984
	v_rcp_f32_e32 v87, v85
	v_mul_f32_e32 v85, v85, v98
	v_cvt_pk_bf16_f32 v85, v85, s0
	v_pk_mul_f32 v[86:87], v[88:89], v[86:87]
	s_nop 0
	v_cvt_pk_bf16_f32 v88, v86, s0
	ds_write_b16 v153, v88 offset:50176
	ds_write_b16 v154, v85 offset:41984
	v_cvt_pk_bf16_f32 v85, v87, s0
	v_pk_mul_f32 v[86:87], v[90:91], v[86:87] op_sel_hi:[0,1]
	ds_write_b16 v154, v85 offset:50176
	v_cvt_pk_bf16_f32 v85, v86, v87
	v_add_u32_e32 v86, v135, v136
	s_waitcnt vmcnt(0)
	ds_write_b128 v86, v[82:85] offset:58368
	s_and_saveexec_b64 vcc, s[0:1]
	s_cbranch_execz .LBB0_406
	v_exp_f32_e32 v81, v81
	v_exp_f32_e32 v80, v80
	v_add_u32_e32 v82, 0x11400, v115
	ds_write_b32 v82, v81
	v_add_u32_e32 v81, 0x11600, v115
	ds_write_b32 v81, v80
